# per-XCD tile-round re-alignment (capped poll on a per-XCD counter) after each of the first four tiles in the w_in and FFN2 gate/up GEMM phases
# speedup vs baseline: 1.0043x; 1.0011x over previous
; #define PG8_STAGE(bufoff, gbase, voff) do { _Pragma("unroll") for (int _i = 0; _i < 2; ++_i) \
;         __builtin_amdgcn_global_load_lds((const unsigned*)((const char*)(gbase) + (voff)[_i]), (LAS unsigned*)(lds + (bufoff) + ldsw + _i * 8192), 16, 0, 0); } while (0)
; #define PG8_WAIT_V(n) asm volatile("s_waitcnt vmcnt(" #n ")" ::: "memory")
; #define PG8_BAR __builtin_amdgcn_s_barrier()
; template <class Sched, class Epi, bool ALIGN_EPI, bool SP2>
; __device__ __forceinline__ void gemm_phase(LAS unsigned char* lds, const int K, const int lda, const int ldb, const Sched& S, const Epi& E) {
;     ...
;     for (int i = 0; i < 2; ++i) { int R, C; stage_rc(tid * 16 + i * 8192, R, C); const int Rb = Epi::PERM ? ((R & ~31) + perm32(R & 31)) : R;
;         voffA[i] = (unsigned)(R * lda + C) * 2u; voffB[i] = (unsigned)(Rb * ldb + C) * 2u; }
;     const size_t kstep = (size_t)(BK * 2);
;     const size_t hstepA = (size_t)HALF * lda * 2, hstepB = (size_t)HALF * ldb * 2;
;     const unsigned ldsw = (unsigned)wid * 1024u;
;     const int aoff = lds_byte(wr * 64 + fr, fq * 8), boff = lds_byte(wc * 32 + fr, fq * 8);
;     ...
;     Unit cur, nxt; int ui = 0;
;     if (!S.next(0, cur)) return;
;     f32x4 acc[2][2][4][2];
; #pragma unroll
;     for (int a = 0; a < 2; ++a)
; #pragma unroll
;         for (int b = 0; b < 2; ++b)
; #pragma unroll
;             for (int m = 0; m < 4; ++m)
; #pragma unroll
;                 for (int n = 0; n < 2; ++n) acc[a][b][m][n] = (f32x4){0.f, 0.f, 0.f, 0.f};
;     bf16x8 At[4][2], B0[2][2], B1[2][2];
;     const char* cA = cur.A; const char* cB = cur.B;
;     if constexpr (SP2) {
;         PG8_STAGE(PG8_SB(0, 0), cB, voffB); PG8_STAGE(PG8_SB(0, 1), cB + hstepB, voffB); PG8_STAGE(PG8_SA(0, 0), cA, voffA); PG8_STAGE(PG8_SA(0, 1), cA + hstepA, voffA);
;         if (wr == 1) PG8_BAR;
;         PG8_WAIT_V(2); PG8_BAR;
;         PG8_STAGE(PG8_SB(1, 0), cB + kstep, voffB); PG8_STAGE(PG8_SA(1, 0), cA + kstep, voffA); PG8_STAGE(PG8_SB(1, 1), cB + hstepB + kstep, voffB);
;         PG8_WAIT_V(6); PG8_BAR;
.LBB0_336:
	v_lshrrev_b32_e32 v16, 1, v8
	v_and_b32_e32 v16, 24, v16
	s_add_u32 s70, s92, 0x2b1a3600
	v_and_b32_e32 v15, 15, v8
	v_lshlrev_b32_e32 v17, 1, v16
	v_lshlrev_b32_e32 v8, 2, v8
	s_addc_u32 s71, s93, 0
	v_lshl_or_b32 v177, s1, 6, v15
	v_lshl_or_b32 v15, v15, 6, v17
	s_lshl_b32 s1, s1, 13
	v_and_b32_e32 v8, 32, v8
	v_bitop3_b32 v17, v15, s1, v8 bitop3:0xde
	s_lshl_b32 s1, s4, 5
	s_mov_b64 s[10:11], 0x80
	s_and_b32 s1, s1, 0x60
	s_add_i32 m0, s89, 0x18000
	v_lshl_add_u64 v[6:7], v[6:7], 0, s[10:11]
	s_lshl_b32 s4, s1, 7
	s_waitcnt vmcnt(2)
	s_barrier
	global_load_lds_dwordx4 v[6:7], off
	v_lshl_add_u64 v[4:5], v[4:5], 0, s[10:11]
	s_add_i32 m0, s89, 0x1a000
	s_add_i32 s97, s89, 0x8000
	s_add_i32 s84, s89, 0xa000
	global_load_lds_dwordx4 v[4:5], off
	v_lshl_add_u64 v[0:1], v[0:1], 0, s[10:11]
	s_mov_b32 m0, s97
	s_add_u32 s6, s28, 0x80080
	global_load_lds_dwordx4 v[0:1], off
	v_lshl_add_u64 v[0:1], v[2:3], 0, s[10:11]
	s_mov_b32 m0, s84
	s_addc_u32 s7, s29, 0
	global_load_lds_dwordx4 v[0:1], off
	s_add_i32 m0, s89, 0x1c000
	v_lshl_add_u64 v[0:1], s[6:7], 0, v[186:187]
	global_load_lds_dwordx4 v[0:1], off
	v_lshl_add_u64 v[0:1], s[6:7], 0, v[190:191]
	s_add_i32 m0, s89, 0x1e000
	s_cmpk_lt_u32 s12, 0x100
	global_load_lds_dwordx4 v[0:1], off
	v_lshlrev_b32_e32 v0, 15, v9
	v_and_b32_e32 v0, 0xffff0000, v0
	v_lshl_add_u32 v0, v10, 12, v0
	v_and_b32_e32 v1, 1, v9
	v_lshl_or_b32 v0, v1, 6, v0
	v_lshl_add_u32 v192, v11, 1, v0
	v_lshlrev_b32_e32 v0, 15, v12
	v_and_b32_e32 v0, 0xffff0000, v0
	s_waitcnt vmcnt(6)
	s_cselect_b64 s[12:13], -1, 0
	s_add_u32 s14, s92, 0x2b1ae600
	v_lshl_add_u32 v0, v13, 12, v0
	v_and_b32_e32 v1, 1, v12
	v_bitop3_b32 v183, v15, s4, v8 bitop3:0xde
	s_addc_u32 s15, s93, 0
	v_lshl_or_b32 v0, v1, 6, v0
	s_add_i32 s85, 0, 0x10000
	s_add_i32 s50, 0, 0x14000
	v_or_b32_e32 v210, s1, v16
	v_mov_b32_e32 v193, v187
	v_lshl_add_u32 v194, v14, 1, v0
	v_mov_b32_e32 v195, v187
	v_add_u32_e32 v211, s85, v183
	v_add_u32_e32 v212, s50, v183
	v_add_u32_e32 v213, 0, v17
	s_add_i32 s57, 0, 0x20000
	s_mov_b32 s16, 0x3a000000
	s_mov_b32 s33, 0xf800000
	v_mov_b32_e32 v214, 0x260
	s_movk_i32 s78, 0x5800
	s_mov_b32 s79, 0
	s_barrier
	s_mov_b32 s101, 0
	s_branch .LBB0_339

; #define PG8_BAR __builtin_amdgcn_s_barrier()
; template <class Sched, class Epi, bool ALIGN_EPI, bool SP2>
; __device__ __forceinline__ void gemm_phase(LAS unsigned char* lds, const int K, const int lda, const int ldb, const Sched& S, const Epi& E) {
;     ...
;         if constexpr (ALIGN_EPI) { if (wr == 0) PG8_BAR; }
;         E(acc, cur, wr, wc, fr, fq);
;         if (!has_next) break;
;         bool keep = false;
;         if constexpr (Epi::CAN_KEEP) keep = (cur.kind < 2);
;         if (!keep) {
; #pragma unroll
;         for (int a = 0; a < 2; ++a)
; #pragma unroll
;             for (int b = 0; b < 2; ++b)
; #pragma unroll
;                 for (int m = 0; m < 4; ++m)
; #pragma unroll
;                     for (int n = 0; n < 2; ++n) acc[a][b][m][n] = (f32x4){0.f, 0.f, 0.f, 0.f};
;         }
;         cur = nxt; cA = nA; cB = nB; ++ui;
;         if constexpr (ALIGN_EPI) { if (wr == 1) PG8_BAR; }
;     }
.LBB0_503:
	s_add_i32 s101, s101, 1
	s_cmp_gt_u32 s101, 4
	s_cbranch_scc1 .Lts_skip_p4
	v_readlane_b32 s100, v255, 13
	s_nop 4
	s_cmp_lg_u32 s100, 0
	s_cbranch_scc1 .Lts_wait_p4
	s_mov_b64 s[98:99], exec
	s_mov_b64 exec, 1
	v_mov_b32_e32 v253, 0x26fc0
	ds_read_b32 v253, v253
	s_getreg_b32 s100, hwreg(HW_REG_XCC_ID, 0, 4)
	s_lshl_b32 s100, s100, 8
	s_add_u32 s100, s100, 0x2b1a0040
	v_mov_b32_e32 v252, s100
	s_waitcnt lgkmcnt(0)
	v_readfirstlane_b32 s100, v253
	v_mov_b32_e32 v253, 1
	s_add_i32 vcc_lo, s101, 0
	s_mul_i32 s100, s100, vcc_lo
	global_atomic_add v252, v253, s[92:93]
	s_mov_b32 vcc_lo, 0
.Lts_poll_p4:
	s_sleep 1
	global_load_dword v253, v252, s[92:93] sc1
	s_add_i32 vcc_lo, vcc_lo, 1
	s_waitcnt vmcnt(0)
	v_readfirstlane_b32 vcc_hi, v253
	s_nop 1
	s_cmp_ge_u32 vcc_hi, s100
	s_cbranch_scc1 .Lts_done_p4
	s_cmp_lt_u32 vcc_lo, 400
	s_cbranch_scc1 .Lts_poll_p4
.Lts_done_p4:
	s_mov_b64 exec, s[98:99]
.Lts_wait_p4:
	s_barrier
.Lts_skip_p4:
	s_andn2_b64 vcc, exec, s[68:69]
	s_cbranch_vccnz .LBB0_337
	s_barrier
	s_branch .LBB0_337

; #define PG8_STAGE(bufoff, gbase, voff) do { _Pragma("unroll") for (int _i = 0; _i < 2; ++_i) \
;         __builtin_amdgcn_global_load_lds((const unsigned*)((const char*)(gbase) + (voff)[_i]), (LAS unsigned*)(lds + (bufoff) + ldsw + _i * 8192), 16, 0, 0); } while (0)
; #define PG8_WAIT_V(n) asm volatile("s_waitcnt vmcnt(" #n ")" ::: "memory")
; #define PG8_BAR __builtin_amdgcn_s_barrier()
; template <class Sched, class Epi, bool ALIGN_EPI, bool SP2>
; __device__ __forceinline__ void gemm_phase(LAS unsigned char* lds, const int K, const int lda, const int ldb, const Sched& S, const Epi& E) {
;     ...
;     for (int i = 0; i < 2; ++i) { int R, C; stage_rc(tid * 16 + i * 8192, R, C); const int Rb = Epi::PERM ? ((R & ~31) + perm32(R & 31)) : R;
;         voffA[i] = (unsigned)(R * lda + C) * 2u; voffB[i] = (unsigned)(Rb * ldb + C) * 2u; }
;     const size_t kstep = (size_t)(BK * 2);
;     const size_t hstepA = (size_t)HALF * lda * 2, hstepB = (size_t)HALF * ldb * 2;
;     const unsigned ldsw = (unsigned)wid * 1024u;
;     const int aoff = lds_byte(wr * 64 + fr, fq * 8), boff = lds_byte(wc * 32 + fr, fq * 8);
;     ...
;     Unit cur, nxt; int ui = 0;
;     if (!S.next(0, cur)) return;
;     f32x4 acc[2][2][4][2];
; #pragma unroll
;     for (int a = 0; a < 2; ++a)
; #pragma unroll
;         for (int b = 0; b < 2; ++b)
; #pragma unroll
;             for (int m = 0; m < 4; ++m)
; #pragma unroll
;                 for (int n = 0; n < 2; ++n) acc[a][b][m][n] = (f32x4){0.f, 0.f, 0.f, 0.f};
;     bf16x8 At[4][2], B0[2][2], B1[2][2];
;     const char* cA = cur.A; const char* cB = cur.B;
;     if constexpr (SP2) {
;         PG8_STAGE(PG8_SB(0, 0), cB, voffB); PG8_STAGE(PG8_SB(0, 1), cB + hstepB, voffB); PG8_STAGE(PG8_SA(0, 0), cA, voffA); PG8_STAGE(PG8_SA(0, 1), cA + hstepA, voffA);
;         if (wr == 1) PG8_BAR;
;         PG8_WAIT_V(2); PG8_BAR;
;         PG8_STAGE(PG8_SB(1, 0), cB + kstep, voffB); PG8_STAGE(PG8_SA(1, 0), cA + kstep, voffA); PG8_STAGE(PG8_SB(1, 1), cB + hstepB + kstep, voffB);
;         PG8_WAIT_V(6); PG8_BAR;
.LBB0_1027:
	s_add_u32 s12, s92, 0x2b1b9600
	s_addc_u32 s13, s93, 0
	s_lshl_b32 s1, s14, 5
	s_mov_b64 s[14:15], 0x80
	s_and_b32 s20, s1, 0x60
	s_add_i32 m0, s33, 0x18000
	v_lshl_add_u64 v[6:7], v[6:7], 0, s[14:15]
	s_lshl_b32 s19, s18, 13
	s_lshl_b32 s24, s20, 7
	s_waitcnt vmcnt(2)
	s_barrier
	global_load_lds_dwordx4 v[6:7], off
	v_lshl_add_u64 v[4:5], v[4:5], 0, s[14:15]
	s_add_i32 m0, s33, 0x1a000
	s_add_i32 s49, s33, 0x8000
	s_add_i32 s50, s33, 0xa000
	global_load_lds_dwordx4 v[4:5], off
	v_lshl_add_u64 v[0:1], v[0:1], 0, s[14:15]
	s_mov_b32 m0, s49
	s_add_u32 s22, s42, 0x80080
	global_load_lds_dwordx4 v[0:1], off
	v_lshl_add_u64 v[0:1], v[2:3], 0, s[14:15]
	s_mov_b32 m0, s50
	s_addc_u32 s23, s43, 0
	global_load_lds_dwordx4 v[0:1], off
	s_add_i32 m0, s33, 0x1c000
	v_lshl_add_u64 v[0:1], s[22:23], 0, v[150:151]
	global_load_lds_dwordx4 v[0:1], off
	v_lshl_add_u64 v[0:1], s[22:23], 0, v[154:155]
	s_add_i32 m0, s33, 0x1e000
	s_cmpk_lt_u32 s17, 0x100
	global_load_lds_dwordx4 v[0:1], off
	v_lshrrev_b32_e32 v1, 1, v8
	v_and_b32_e32 v1, 24, v1
	v_and_b32_e32 v0, 15, v8
	v_lshlrev_b32_e32 v2, 1, v1
	v_lshl_or_b32 v177, s18, 6, v0
	v_lshl_or_b32 v0, v0, 6, v2
	v_lshlrev_b32_e32 v2, 2, v8
	v_and_b32_e32 v2, 32, v2
	v_bitop3_b32 v3, v0, s19, v2 bitop3:0xde
	v_bitop3_b32 v181, v0, s24, v2 bitop3:0xde
	v_lshlrev_b32_e32 v0, 15, v9
	v_and_b32_e32 v0, 0xffff0000, v0
	v_or_b32_e32 v182, s20, v1
	v_lshl_add_u32 v0, v10, 12, v0
	v_and_b32_e32 v1, 1, v9
	v_lshl_or_b32 v0, v1, 6, v0
	v_lshl_add_u32 v156, v11, 1, v0
	v_lshlrev_b32_e32 v0, 15, v12
	v_and_b32_e32 v0, 0xffff0000, v0
	s_sext_i32_i16 s1, s16
	s_waitcnt vmcnt(6)
	s_cselect_b64 s[16:17], -1, 0
	s_add_u32 s18, s92, 0x2b1c4600
	v_lshl_add_u32 v0, v13, 12, v0
	v_and_b32_e32 v1, 1, v12
	s_addc_u32 s19, s93, 0
	v_lshl_or_b32 v0, v1, 6, v0
	s_add_i32 s51, 0, 0x10000
	s_add_i32 s52, 0, 0x14000
	v_mov_b32_e32 v157, v151
	v_lshl_add_u32 v158, v14, 1, v0
	v_mov_b32_e32 v159, v151
	v_add_u32_e32 v183, s51, v181
	v_add_u32_e32 v184, s52, v181
	v_add_u32_e32 v185, 0, v3
	s_movk_i32 s53, 0x2c00
	s_mov_b32 s20, 0x3a000000
	s_mov_b32 s54, 0xf800000
	v_mov_b32_e32 v186, 0x260
	s_mov_b64 s[26:27], s[36:37]
	s_mov_b64 s[28:29], s[42:43]
	s_barrier
	s_mov_b32 s101, 0
	s_branch .LBB0_1030

; __device__ __forceinline__ unsigned cvt_pk_bf16(float lo, float hi) { unsigned r; asm volatile("v_cvt_pk_bf16_f32 %0, %1, %2" : "=v"(r) : "v"(lo), "v"(hi)); return r; }
; __device__ __forceinline__ float siluf_(float x) { return x * sigmoidf_(x); }
; __device__ __forceinline__ f32x2 ln_stats(f32x2 sm) { const float mu = sm[0] * (1.f / D); const float var = fmaxf(sm[1] * (1.f / D) - mu * mu, 0.f); return (f32x2){mu, 1.0f / sqrtf(var + LN_EPS)}; }
;     __device__ __forceinline__ void operator()(const f32x4 (&acc)[2][2][4][2], const Unit& u, int wr, int wc, int fr, int fq) const {
;         const int row0 = u.pm * BM + wr * 64 + fr, col0 = u.pn * HALF + wc * 32 + 8 * fq;
;         f32x4 s1[2][2], s2[2][2];
; #pragma unroll
;         for (int bj = 0; bj < 2; ++bj)
; #pragma unroll
;             for (int n = 0; n < 2; ++n) { s1[bj][n] = (f32x4){0.f, 0.f, 0.f, 0.f}; s2[bj][n] = s1[bj][n];
;                 if (rsum) { const int ci = u.pn * BM + bj * HALF + wc * 32 + 8 * fq + 4 * n; s1[bj][n] = *(const f32x4*)(cs + ci); s2[bj][n] = *(const f32x4*)(cs + NZ + ci); } }
; #pragma unroll
;         for (int ai = 0; ai < 2; ++ai)
; #pragma unroll
;             for (int m = 0; m < 4; ++m) {
;                 const int r = row0 + ai * HALF + m * 16;
;                 bf16_t* rowp = H + (size_t)r * ldh + col0;
;                 f32x2 st = (f32x2){0.f, 1.f};
;                 if (rsum) st = ln_stats(*(const f32x2*)(rsum + 2 * (size_t)r));
;                 f32x4 v0, v1;
; #pragma unroll
;                 for (int j = 0; j < 4; ++j) {
;                     const float g0 = st[1] * (acc[ai][0][m][0][j] - st[0] * s1[0][0][j]) + s2[0][0][j], u0 = st[1] * (acc[ai][1][m][0][j] - st[0] * s1[1][0][j]) + s2[1][0][j];
;                     const float g1 = st[1] * (acc[ai][0][m][1][j] - st[0] * s1[0][1][j]) + s2[0][1][j], u1 = st[1] * (acc[ai][1][m][1][j] - st[0] * s1[1][1][j]) + s2[1][1][j];
;                     v0[j] = siluf_(g0) * u0; v1[j] = siluf_(g1) * u1;
;                 }
;                 u32x4 w; w.x = cvt_pk_bf16(v0[0], v0[1]); w.y = cvt_pk_bf16(v0[2], v0[3]); w.z = cvt_pk_bf16(v1[0], v1[1]); w.w = cvt_pk_bf16(v1[2], v1[3]);
;                 *(u32x4*)rowp = w;
;             }
.LBB0_1040:
	v_lshl_or_b32 v144, s1, 8, v182
	v_lshl_add_u32 v162, s0, 8, v177
	v_ashrrev_i32_e32 v145, 31, v144
	v_lshlrev_b64 v[64:65], 2, v[144:145]
	v_ashrrev_i32_e32 v163, 31, v162
	v_lshl_add_u64 v[68:69], s[18:19], 0, v[64:65]
	v_lshl_add_u64 v[70:71], s[12:13], 0, v[64:65]
	v_lshl_add_u64 v[64:65], v[162:163], 3, s[8:9]
	global_load_dwordx2 v[164:165], v[64:65], off
	global_load_dwordx2 v[238:239], v[64:65], off offset:128
	global_load_dwordx2 v[240:241], v[64:65], off offset:256
	global_load_dwordx2 v[242:243], v[64:65], off offset:384
	global_load_dwordx2 v[244:245], v[64:65], off offset:1024
	global_load_dwordx2 v[246:247], v[64:65], off offset:1152
	global_load_dwordx2 v[248:249], v[64:65], off offset:1280
	global_load_dwordx2 v[250:251], v[64:65], off offset:1408
	s_nop 0
	global_load_dwordx4 v[64:67], v[70:71], off offset:16
	global_load_dwordx4 v[76:79], v[70:71], off
	global_load_dwordx4 v[72:75], v[68:69], off
	s_nop 0
	global_load_dwordx4 v[68:71], v[68:69], off offset:16
	v_or_b32_e32 v144, 0x80, v144
	v_ashrrev_i32_e32 v145, 31, v144
	v_lshlrev_b64 v[144:145], 2, v[144:145]
	v_lshl_add_u64 v[146:147], s[18:19], 0, v[144:145]
	v_lshl_add_u64 v[144:145], s[12:13], 0, v[144:145]
	global_load_dwordx4 v[188:191], v[144:145], off
	global_load_dwordx4 v[192:195], v[146:147], off
	global_load_dwordx4 v[196:199], v[144:145], off offset:16
	s_nop 0
	global_load_dwordx4 v[144:147], v[146:147], off offset:16
	v_lshl_or_b32 v166, s1, 7, v182
	v_mov_b64_e32 v[160:161], s[40:41]
	v_ashrrev_i32_e32 v167, 31, v166
	v_mov_b32_e32 v202, v128
	v_mov_b32_e32 v203, v136
	v_mov_b32_e32 v136, v129
	v_mad_i64_i32 v[128:129], s[0:1], v162, s53, v[160:161]
	v_lshlrev_b64 v[170:171], 1, v[166:167]
	v_lshl_add_u64 v[208:209], v[128:129], 0, v[170:171]
	v_mov_b32_e32 v204, v134
	v_mov_b32_e32 v206, v130
	v_mov_b32_e32 v207, v138
	v_mov_b32_e32 v200, v132
	v_mov_b32_e32 v201, v140
	v_mov_b32_e32 v140, v133
	v_mov_b32_e32 v205, v142
	v_mov_b32_e32 v142, v135
	s_waitcnt vmcnt(0)
	v_pk_mul_f32 v[210:211], v[164:165], s[20:21] op_sel_hi:[1,0]
	s_nop 0
	v_fma_f32 v128, -v210, v210, v211
	v_mov_b32_e32 v169, v66
	v_max_f32_e32 v66, 0, v128
	v_add_f32_e32 v66, 0x3727c5ac, v66
	v_mov_b32_e32 v129, v74
	v_mul_f32_e32 v74, 0x4f800000, v66
	v_cmp_gt_f32_e32 vcc, s54, v66
	v_mov_b32_e32 v167, v78
	v_mov_b32_e32 v173, v76
	v_cndmask_b32_e32 v66, v66, v74, vcc
	v_sqrt_f32_e32 v74, v66
	v_mov_b32_e32 v172, v188
	v_mov_b32_e32 v133, v72
	v_mov_b32_e32 v165, v68
	v_add_u32_e32 v78, -1, v74
	v_add_u32_e32 v130, 1, v74
	v_fma_f32 v134, -v78, v74, v66
	v_fma_f32 v138, -v130, v74, v66
	v_cmp_ge_f32_e64 s[0:1], 0, v134
	v_mov_b32_e32 v132, v192
	v_mov_b32_e32 v164, v144
	v_cndmask_b32_e64 v74, v74, v78, s[0:1]
	v_cmp_lt_f32_e64 s[0:1], 0, v138
	v_mov_b32_e32 v68, v145
	v_pk_fma_f32 v[144:145], v[172:173], v[210:211], v[200:201] op_sel_hi:[1,0,1] neg_lo:[1,0,0] neg_hi:[1,0,0]
	v_cndmask_b32_e64 v74, v74, v130, s[0:1]
	v_mul_f32_e32 v78, 0x37800000, v74
	v_cndmask_b32_e32 v74, v74, v78, vcc
	v_cmp_class_f32_e32 vcc, v66, v186
	v_mov_b32_e32 v76, v189
	v_mov_b32_e32 v72, v193
	v_cndmask_b32_e32 v66, v74, v66, vcc
	v_div_scale_f32 v74, s[0:1], v66, v66, 1.0
	v_rcp_f32_e32 v78, v74
	v_div_scale_f32 v130, vcc, 1.0, v66, 1.0
	v_pk_fma_f32 v[140:141], v[76:77], v[210:211], v[140:141] op_sel_hi:[1,0,1] neg_lo:[1,0,0] neg_hi:[1,0,0]
	v_fma_f32 v134, -v74, v78, 1.0
	v_fmac_f32_e32 v78, v134, v78
	v_mul_f32_e32 v134, v130, v78
	v_fma_f32 v138, -v74, v134, v130
	v_fmac_f32_e32 v134, v138, v78
	v_fma_f32 v74, -v74, v134, v130
	v_div_fmas_f32 v74, v74, v78, v134
	v_div_fixup_f32 v130, v74, v66, 1.0
	v_pk_fma_f32 v[144:145], v[144:145], v[130:131], v[132:133] op_sel_hi:[1,0,1]
	v_pk_fma_f32 v[140:141], v[140:141], v[130:131], v[72:73] op_sel_hi:[1,0,1]
	v_mul_f32_e32 v66, 0xbfb8aa3b, v145
	v_exp_f32_e32 v66, v66
	v_mul_f32_e32 v78, 0xbfb8aa3b, v141
	v_exp_f32_e32 v78, v78
	v_mov_b32_e32 v166, v190
	v_add_f32_e32 v66, 1.0, v66
	v_rcp_f32_e32 v66, v66
	v_mov_b32_e32 v175, v64
	v_mov_b32_e32 v174, v196
	v_mov_b32_e32 v64, v197
	v_mov_b32_e32 v128, v194
	v_pk_fma_f32 v[192:193], v[166:167], v[210:211], v[204:205] op_sel_hi:[1,0,1] neg_lo:[1,0,0] neg_hi:[1,0,0]
	v_pk_fma_f32 v[188:189], v[174:175], v[210:211], v[202:203] op_sel_hi:[1,0,1] neg_lo:[1,0,0] neg_hi:[1,0,0]
	v_pk_fma_f32 v[136:137], v[64:65], v[210:211], v[136:137] op_sel_hi:[1,0,1] neg_lo:[1,0,0] neg_hi:[1,0,0]
	v_pk_fma_f32 v[192:193], v[192:193], v[130:131], v[128:129] op_sel_hi:[1,0,1]
	v_add_f32_e32 v78, 1.0, v78
	v_pk_fma_f32 v[188:189], v[188:189], v[130:131], v[164:165] op_sel_hi:[1,0,1]
	v_pk_fma_f32 v[200:201], v[136:137], v[130:131], v[68:69] op_sel_hi:[1,0,1]
	v_mul_f32_e32 v136, 0xbfb8aa3b, v193
	v_rcp_f32_e32 v78, v78
	v_mul_f32_e32 v66, v145, v66
	v_mul_f32_e32 v74, 0xbfb8aa3b, v189
	v_mul_f32_e32 v144, v144, v66
	v_exp_f32_e32 v66, v136
	v_mul_f32_e32 v134, 0xbfb8aa3b, v201
	v_exp_f32_e32 v74, v74
	v_mov_b32_e32 v168, v198
	v_exp_f32_e32 v134, v134
	v_pk_fma_f32 v[196:197], v[168:169], v[210:211], v[206:207] op_sel_hi:[1,0,1] neg_lo:[1,0,0] neg_hi:[1,0,0]
	v_mul_f32_e32 v78, v141, v78
	v_mov_b32_e32 v136, v146
	v_mov_b32_e32 v137, v70
	v_mul_f32_e32 v163, v140, v78
	v_pk_fma_f32 v[140:141], v[196:197], v[130:131], v[136:137] op_sel_hi:[1,0,1]
	v_add_f32_e32 v66, 1.0, v66
	v_add_f32_e32 v74, 1.0, v74
	v_rcp_f32_e32 v66, v66
	v_mul_f32_e32 v70, 0xbfb8aa3b, v141
	v_add_f32_e32 v134, 1.0, v134
	v_rcp_f32_e32 v74, v74
	v_exp_f32_e32 v70, v70
	v_rcp_f32_e32 v134, v134
	v_mul_f32_e32 v66, v193, v66
	v_mul_f32_e32 v74, v189, v74
	v_mul_f32_e32 v187, v192, v66
	v_add_f32_e32 v66, 1.0, v70
	v_mul_f32_e32 v134, v201, v134
; __device__ __forceinline__ unsigned cvt_pk_bf16(float lo, float hi) { unsigned r; asm volatile("v_cvt_pk_bf16_f32 %0, %1, %2" : "=v"(r) : "v"(lo), "v"(hi)); return r; }
; __device__ __forceinline__ float siluf_(float x) { return x * sigmoidf_(x); }
; __device__ __forceinline__ f32x2 ln_stats(f32x2 sm) { const float mu = sm[0] * (1.f / D); const float var = fmaxf(sm[1] * (1.f / D) - mu * mu, 0.f); return (f32x2){mu, 1.0f / sqrtf(var + LN_EPS)}; }
;     __device__ __forceinline__ void operator()(const f32x4 (&acc)[2][2][4][2], const Unit& u, int wr, int wc, int fr, int fq) const {
;     ...
;         for (int ai = 0; ai < 2; ++ai)
; #pragma unroll
;             for (int m = 0; m < 4; ++m) {
;                 const int r = row0 + ai * HALF + m * 16;
;                 bf16_t* rowp = H + (size_t)r * ldh + col0;
;                 f32x2 st = (f32x2){0.f, 1.f};
;                 if (rsum) st = ln_stats(*(const f32x2*)(rsum + 2 * (size_t)r));
;                 f32x4 v0, v1;
; #pragma unroll
;                 for (int j = 0; j < 4; ++j) {
;                     const float g0 = st[1] * (acc[ai][0][m][0][j] - st[0] * s1[0][0][j]) + s2[0][0][j], u0 = st[1] * (acc[ai][1][m][0][j] - st[0] * s1[1][0][j]) + s2[1][0][j];
;                     const float g1 = st[1] * (acc[ai][0][m][1][j] - st[0] * s1[0][1][j]) + s2[0][1][j], u1 = st[1] * (acc[ai][1][m][1][j] - st[0] * s1[1][1][j]) + s2[1][1][j];
;                     v0[j] = siluf_(g0) * u0; v1[j] = siluf_(g1) * u1;
;                 }
;                 u32x4 w; w.x = cvt_pk_bf16(v0[0], v0[1]); w.y = cvt_pk_bf16(v0[2], v0[3]); w.z = cvt_pk_bf16(v1[0], v1[1]); w.w = cvt_pk_bf16(v1[2], v1[3]);
;                 *(u32x4*)rowp = w;
	v_mul_f32_e32 v145, v188, v74
	v_rcp_f32_e32 v188, v66
	v_mov_b32_e32 v78, v191
	v_mov_b32_e32 v66, v199
	v_mov_b32_e32 v138, v131
	v_mul_f32_e32 v146, v200, v134
	v_pk_fma_f32 v[134:135], v[78:79], v[210:211], v[142:143] op_sel_hi:[1,0,1] neg_lo:[1,0,0] neg_hi:[1,0,0]
	v_mov_b32_e32 v74, v195
	v_pk_fma_f32 v[138:139], v[66:67], v[210:211], v[138:139] op_sel_hi:[1,0,1] neg_lo:[1,0,0] neg_hi:[1,0,0]
	v_mov_b32_e32 v70, v147
	v_pk_fma_f32 v[134:135], v[134:135], v[130:131], v[74:75] op_sel_hi:[1,0,1]
	v_pk_fma_f32 v[130:131], v[138:139], v[130:131], v[70:71] op_sel_hi:[1,0,1]
	v_mul_f32_e32 v138, 0xbfb8aa3b, v135
	v_mul_f32_e32 v139, 0xbfb8aa3b, v131
	v_exp_f32_e32 v139, v139
	v_exp_f32_e32 v138, v138
	v_mul_f32_e32 v141, v141, v188
	v_mul_f32_e32 v141, v140, v141
	v_add_f32_e32 v139, 1.0, v139
	v_add_f32_e32 v138, 1.0, v138
	v_rcp_f32_e32 v139, v139
	v_rcp_f32_e32 v138, v138
	v_mul_f32_e32 v131, v131, v139
	v_mul_f32_e32 v135, v135, v138
	v_mul_f32_e32 v130, v130, v131
	v_mul_f32_e32 v134, v134, v135
	v_cvt_pk_bf16_f32 v138, v144, v163
	v_cvt_pk_bf16_f32 v139, v187, v134
	v_cvt_pk_bf16_f32 v140, v145, v146
	v_cvt_pk_bf16_f32 v141, v141, v130
	v_or_b32_e32 v130, 16, v162
	v_ashrrev_i32_e32 v131, 31, v130
	global_store_dwordx4 v[208:209], v[138:141], off
	v_lshl_add_u64 v[134:135], v[130:131], 3, s[8:9]
	v_mov_b32_e32 v134, v238
	v_mov_b32_e32 v135, v239
	v_mov_b32_e32 v138, v116
	v_mov_b32_e32 v116, v114
	v_mov_b32_e32 v139, v124
	v_mov_b32_e32 v124, v117
	v_mov_b32_e32 v140, v112
	v_mov_b32_e32 v112, v118
	v_mov_b32_e32 v141, v120
	v_mov_b32_e32 v120, v113
	v_mov_b32_e32 v113, v126
	v_mad_i64_i32 v[130:131], s[0:1], v130, s53, v[160:161]
	v_lshl_add_u64 v[130:131], v[130:131], 0, v[170:171]
	s_nop 0
	v_pk_mul_f32 v[134:135], v[134:135], s[20:21] op_sel_hi:[1,0]
	s_nop 0
	v_fma_f32 v114, -v134, v134, v135
	v_max_f32_e32 v114, 0, v114
	v_add_f32_e32 v114, 0x3727c5ac, v114
	v_mul_f32_e32 v117, 0x4f800000, v114
	v_cmp_gt_f32_e32 vcc, s54, v114
	v_pk_fma_f32 v[138:139], v[172:173], v[134:135], v[138:139] op_sel_hi:[1,0,1] neg_lo:[1,0,0] neg_hi:[1,0,0]
	v_pk_fma_f32 v[140:141], v[174:175], v[134:135], v[140:141] op_sel_hi:[1,0,1] neg_lo:[1,0,0] neg_hi:[1,0,0]
	v_cndmask_b32_e32 v114, v114, v117, vcc
	v_sqrt_f32_e32 v117, v114
	v_pk_fma_f32 v[120:121], v[64:65], v[134:135], v[120:121] op_sel_hi:[1,0,1] neg_lo:[1,0,0] neg_hi:[1,0,0]
	v_pk_fma_f32 v[112:113], v[166:167], v[134:135], v[112:113] op_sel_hi:[1,0,1] neg_lo:[1,0,0] neg_hi:[1,0,0]
	v_pk_fma_f32 v[124:125], v[76:77], v[134:135], v[124:125] op_sel_hi:[1,0,1] neg_lo:[1,0,0] neg_hi:[1,0,0]
	v_add_u32_e32 v118, -1, v117
	v_add_u32_e32 v126, 1, v117
	v_fma_f32 v142, -v118, v117, v114
	v_fma_f32 v143, -v126, v117, v114
	v_cmp_ge_f32_e64 s[0:1], 0, v142
	s_nop 1
	v_cndmask_b32_e64 v117, v117, v118, s[0:1]
	v_cmp_lt_f32_e64 s[0:1], 0, v143
	s_nop 1
	v_cndmask_b32_e64 v117, v117, v126, s[0:1]
	v_mul_f32_e32 v118, 0x37800000, v117
	v_cndmask_b32_e32 v117, v117, v118, vcc
	v_cmp_class_f32_e32 vcc, v114, v186
	s_nop 1
	v_cndmask_b32_e32 v114, v117, v114, vcc
	v_div_scale_f32 v117, s[0:1], v114, v114, 1.0
	v_rcp_f32_e32 v118, v117
	v_div_scale_f32 v126, vcc, 1.0, v114, 1.0
	v_fma_f32 v142, -v117, v118, 1.0
	v_fmac_f32_e32 v118, v142, v118
	v_mul_f32_e32 v142, v126, v118
	v_fma_f32 v143, -v117, v142, v126
	v_fmac_f32_e32 v142, v143, v118
	v_fma_f32 v117, -v117, v142, v126
	v_div_fmas_f32 v117, v117, v118, v142
	v_div_fixup_f32 v114, v117, v114, 1.0
	v_pk_fma_f32 v[138:139], v[138:139], v[114:115], v[132:133] op_sel_hi:[1,0,1]
	v_pk_fma_f32 v[140:141], v[140:141], v[114:115], v[164:165] op_sel_hi:[1,0,1]
	v_mul_f32_e32 v117, 0xbfb8aa3b, v139
	v_mul_f32_e32 v118, 0xbfb8aa3b, v141
	v_exp_f32_e32 v117, v117
	v_exp_f32_e32 v118, v118
	v_pk_fma_f32 v[120:121], v[120:121], v[114:115], v[68:69] op_sel_hi:[1,0,1]
	v_pk_fma_f32 v[112:113], v[112:113], v[114:115], v[128:129] op_sel_hi:[1,0,1]
	v_add_f32_e32 v117, 1.0, v117
	v_add_f32_e32 v118, 1.0, v118
	v_rcp_f32_e32 v117, v117
	v_rcp_f32_e32 v118, v118
	v_pk_fma_f32 v[124:125], v[124:125], v[114:115], v[72:73] op_sel_hi:[1,0,1]
	v_mul_f32_e32 v142, 0xbfb8aa3b, v121
	v_mul_f32_e32 v117, v139, v117
	v_mul_f32_e32 v118, v141, v118
	v_mul_f32_e32 v138, v138, v117
	v_mul_f32_e32 v117, 0xbfb8aa3b, v113
	v_mul_f32_e32 v126, 0xbfb8aa3b, v125
	v_exp_f32_e32 v142, v142
	v_mul_f32_e32 v139, v140, v118
	v_exp_f32_e32 v118, v117
	v_exp_f32_e32 v126, v126
	v_mov_b32_e32 v117, v122
	v_pk_fma_f32 v[116:117], v[168:169], v[134:135], v[116:117] op_sel_hi:[1,0,1] neg_lo:[1,0,0] neg_hi:[1,0,0]
	v_add_f32_e32 v142, 1.0, v142
	v_pk_fma_f32 v[116:117], v[116:117], v[114:115], v[136:137] op_sel_hi:[1,0,1]
	v_add_f32_e32 v118, 1.0, v118
	v_add_f32_e32 v126, 1.0, v126
	v_rcp_f32_e32 v142, v142
	v_rcp_f32_e32 v118, v118
	v_mul_f32_e32 v122, 0xbfb8aa3b, v117
	v_rcp_f32_e32 v126, v126
	v_exp_f32_e32 v122, v122
	v_mul_f32_e32 v121, v121, v142
	v_mul_f32_e32 v113, v113, v118
	v_mul_f32_e32 v125, v125, v126
	v_mul_f32_e32 v120, v120, v121
	v_mul_f32_e32 v121, v112, v113
	v_add_f32_e32 v112, 1.0, v122
	v_mov_b32_e32 v126, v119
	v_mul_f32_e32 v124, v124, v125
	v_rcp_f32_e32 v125, v112
	v_pk_fma_f32 v[112:113], v[78:79], v[134:135], v[126:127] op_sel_hi:[1,0,1] neg_lo:[1,0,0] neg_hi:[1,0,0]
	v_mov_b32_e32 v122, v115
	v_pk_fma_f32 v[112:113], v[112:113], v[114:115], v[74:75] op_sel_hi:[1,0,1]
	v_pk_fma_f32 v[118:119], v[66:67], v[134:135], v[122:123] op_sel_hi:[1,0,1] neg_lo:[1,0,0] neg_hi:[1,0,0]
	v_mul_f32_e32 v117, v117, v125
	v_pk_fma_f32 v[114:115], v[118:119], v[114:115], v[70:71] op_sel_hi:[1,0,1]
	v_mul_f32_e32 v118, 0xbfb8aa3b, v113
	v_exp_f32_e32 v118, v118
	v_mul_f32_e32 v119, 0xbfb8aa3b, v115
; __device__ __forceinline__ unsigned cvt_pk_bf16(float lo, float hi) { unsigned r; asm volatile("v_cvt_pk_bf16_f32 %0, %1, %2" : "=v"(r) : "v"(lo), "v"(hi)); return r; }
; __device__ __forceinline__ float siluf_(float x) { return x * sigmoidf_(x); }
; __device__ __forceinline__ f32x2 ln_stats(f32x2 sm) { const float mu = sm[0] * (1.f / D); const float var = fmaxf(sm[1] * (1.f / D) - mu * mu, 0.f); return (f32x2){mu, 1.0f / sqrtf(var + LN_EPS)}; }
;     __device__ __forceinline__ void operator()(const f32x4 (&acc)[2][2][4][2], const Unit& u, int wr, int wc, int fr, int fq) const {
;     ...
;         for (int ai = 0; ai < 2; ++ai)
; #pragma unroll
;             for (int m = 0; m < 4; ++m) {
;                 const int r = row0 + ai * HALF + m * 16;
;                 bf16_t* rowp = H + (size_t)r * ldh + col0;
;                 f32x2 st = (f32x2){0.f, 1.f};
;                 if (rsum) st = ln_stats(*(const f32x2*)(rsum + 2 * (size_t)r));
;                 f32x4 v0, v1;
; #pragma unroll
;                 for (int j = 0; j < 4; ++j) {
;                     const float g0 = st[1] * (acc[ai][0][m][0][j] - st[0] * s1[0][0][j]) + s2[0][0][j], u0 = st[1] * (acc[ai][1][m][0][j] - st[0] * s1[1][0][j]) + s2[1][0][j];
;                     const float g1 = st[1] * (acc[ai][0][m][1][j] - st[0] * s1[0][1][j]) + s2[0][1][j], u1 = st[1] * (acc[ai][1][m][1][j] - st[0] * s1[1][1][j]) + s2[1][1][j];
;                     v0[j] = siluf_(g0) * u0; v1[j] = siluf_(g1) * u1;
;                 }
;                 u32x4 w; w.x = cvt_pk_bf16(v0[0], v0[1]); w.y = cvt_pk_bf16(v0[2], v0[3]); w.z = cvt_pk_bf16(v1[0], v1[1]); w.w = cvt_pk_bf16(v1[2], v1[3]);
;                 *(u32x4*)rowp = w;
	v_exp_f32_e32 v119, v119
	v_mul_f32_e32 v116, v116, v117
	v_add_f32_e32 v118, 1.0, v118
	v_rcp_f32_e32 v118, v118
	v_add_f32_e32 v119, 1.0, v119
	v_rcp_f32_e32 v119, v119
	v_mov_b32_e32 v117, v108
	v_mul_f32_e32 v113, v113, v118
	v_mul_f32_e32 v113, v112, v113
	v_mul_f32_e32 v112, v115, v119
	v_mul_f32_e32 v115, v114, v112
	v_cvt_pk_bf16_f32 v112, v138, v124
	v_cvt_pk_bf16_f32 v113, v121, v113
	v_cvt_pk_bf16_f32 v114, v139, v120
	v_cvt_pk_bf16_f32 v115, v116, v115
	global_store_dwordx4 v[130:131], v[112:115], off
	v_mov_b32_e32 v116, v100
	v_mov_b32_e32 v100, v98
	v_or_b32_e32 v112, 32, v162
	v_ashrrev_i32_e32 v113, 31, v112
	v_lshl_add_u64 v[114:115], v[112:113], 3, s[8:9]
	v_mov_b32_e32 v114, v240
	v_mov_b32_e32 v115, v241
	v_mov_b32_e32 v118, v96
	v_mov_b32_e32 v96, v102
	v_mov_b32_e32 v108, v101
	v_mov_b32_e32 v101, v106
	v_mov_b32_e32 v119, v104
	v_mov_b32_e32 v104, v97
	v_mov_b32_e32 v97, v110
	v_mad_i64_i32 v[112:113], s[0:1], v112, s53, v[160:161]
	v_lshl_add_u64 v[112:113], v[112:113], 0, v[170:171]
	s_nop 0
	v_pk_mul_f32 v[114:115], v[114:115], s[20:21] op_sel_hi:[1,0]
	s_nop 0
	v_fma_f32 v98, -v114, v114, v115
	v_max_f32_e32 v98, 0, v98
	v_add_f32_e32 v98, 0x3727c5ac, v98
	v_mul_f32_e32 v102, 0x4f800000, v98
	v_cmp_gt_f32_e32 vcc, s54, v98
	v_pk_fma_f32 v[116:117], v[172:173], v[114:115], v[116:117] op_sel_hi:[1,0,1] neg_lo:[1,0,0] neg_hi:[1,0,0]
	v_pk_fma_f32 v[118:119], v[174:175], v[114:115], v[118:119] op_sel_hi:[1,0,1] neg_lo:[1,0,0] neg_hi:[1,0,0]
	v_cndmask_b32_e32 v98, v98, v102, vcc
	v_sqrt_f32_e32 v102, v98
	v_pk_fma_f32 v[104:105], v[64:65], v[114:115], v[104:105] op_sel_hi:[1,0,1] neg_lo:[1,0,0] neg_hi:[1,0,0]
	v_pk_fma_f32 v[96:97], v[166:167], v[114:115], v[96:97] op_sel_hi:[1,0,1] neg_lo:[1,0,0] neg_hi:[1,0,0]
	v_pk_fma_f32 v[108:109], v[76:77], v[114:115], v[108:109] op_sel_hi:[1,0,1] neg_lo:[1,0,0] neg_hi:[1,0,0]
	v_add_u32_e32 v106, -1, v102
	v_add_u32_e32 v110, 1, v102
	v_fma_f32 v120, -v106, v102, v98
	v_fma_f32 v121, -v110, v102, v98
	v_cmp_ge_f32_e64 s[0:1], 0, v120
	v_pk_fma_f32 v[100:101], v[168:169], v[114:115], v[100:101] op_sel_hi:[1,0,1] neg_lo:[1,0,0] neg_hi:[1,0,0]
	s_nop 0
	v_cndmask_b32_e64 v102, v102, v106, s[0:1]
	v_cmp_lt_f32_e64 s[0:1], 0, v121
	s_nop 1
	v_cndmask_b32_e64 v102, v102, v110, s[0:1]
	v_mul_f32_e32 v106, 0x37800000, v102
	v_cndmask_b32_e32 v102, v102, v106, vcc
	v_cmp_class_f32_e32 vcc, v98, v186
	s_nop 1
	v_cndmask_b32_e32 v98, v102, v98, vcc
	v_div_scale_f32 v102, s[0:1], v98, v98, 1.0
	v_rcp_f32_e32 v106, v102
	v_div_scale_f32 v110, vcc, 1.0, v98, 1.0
	v_fma_f32 v120, -v102, v106, 1.0
	v_fmac_f32_e32 v106, v120, v106
	v_mul_f32_e32 v120, v110, v106
	v_fma_f32 v121, -v102, v120, v110
	v_fmac_f32_e32 v120, v121, v106
	v_fma_f32 v102, -v102, v120, v110
	v_div_fmas_f32 v102, v102, v106, v120
	v_div_fixup_f32 v98, v102, v98, 1.0
	v_pk_fma_f32 v[116:117], v[116:117], v[98:99], v[132:133] op_sel_hi:[1,0,1]
	v_pk_fma_f32 v[118:119], v[118:119], v[98:99], v[164:165] op_sel_hi:[1,0,1]
	v_mul_f32_e32 v102, 0xbfb8aa3b, v117
	v_mul_f32_e32 v106, 0xbfb8aa3b, v119
	v_exp_f32_e32 v102, v102
	v_exp_f32_e32 v106, v106
	v_pk_fma_f32 v[104:105], v[104:105], v[98:99], v[68:69] op_sel_hi:[1,0,1]
	v_pk_fma_f32 v[96:97], v[96:97], v[98:99], v[128:129] op_sel_hi:[1,0,1]
	v_add_f32_e32 v102, 1.0, v102
	v_pk_fma_f32 v[108:109], v[108:109], v[98:99], v[72:73] op_sel_hi:[1,0,1]
	v_mul_f32_e32 v120, 0xbfb8aa3b, v105
	v_mul_f32_e32 v121, 0xbfb8aa3b, v97
	v_add_f32_e32 v106, 1.0, v106
	v_rcp_f32_e32 v102, v102
	v_mul_f32_e32 v110, 0xbfb8aa3b, v109
	v_exp_f32_e32 v120, v120
	v_exp_f32_e32 v121, v121
	v_rcp_f32_e32 v106, v106
	v_exp_f32_e32 v110, v110
	v_mul_f32_e32 v102, v117, v102
	v_add_f32_e32 v120, 1.0, v120
	v_mul_f32_e32 v106, v119, v106
	v_mul_f32_e32 v116, v116, v102
	v_pk_fma_f32 v[100:101], v[100:101], v[98:99], v[136:137] op_sel_hi:[1,0,1]
	v_add_f32_e32 v102, 1.0, v121
	v_add_f32_e32 v110, 1.0, v110
	v_rcp_f32_e32 v120, v120
	v_mul_f32_e32 v117, v118, v106
	v_rcp_f32_e32 v102, v102
	v_mul_f32_e32 v106, 0xbfb8aa3b, v101
	v_rcp_f32_e32 v110, v110
	v_exp_f32_e32 v106, v106
	v_mul_f32_e32 v105, v105, v120
	v_mul_f32_e32 v97, v97, v102
	v_mul_f32_e32 v109, v109, v110
	v_mul_f32_e32 v104, v104, v105
	v_mul_f32_e32 v105, v96, v97
	v_add_f32_e32 v96, 1.0, v106
	v_mov_b32_e32 v110, v103
	v_mul_f32_e32 v108, v108, v109
	v_rcp_f32_e32 v109, v96
	v_pk_fma_f32 v[96:97], v[78:79], v[114:115], v[110:111] op_sel_hi:[1,0,1] neg_lo:[1,0,0] neg_hi:[1,0,0]
	v_mov_b32_e32 v106, v99
	v_pk_fma_f32 v[96:97], v[96:97], v[98:99], v[74:75] op_sel_hi:[1,0,1]
	v_pk_fma_f32 v[102:103], v[66:67], v[114:115], v[106:107] op_sel_hi:[1,0,1] neg_lo:[1,0,0] neg_hi:[1,0,0]
	v_mul_f32_e32 v101, v101, v109
	v_pk_fma_f32 v[98:99], v[102:103], v[98:99], v[70:71] op_sel_hi:[1,0,1]
	v_mul_f32_e32 v102, 0xbfb8aa3b, v97
	v_exp_f32_e32 v102, v102
	v_mul_f32_e32 v103, 0xbfb8aa3b, v99
	v_exp_f32_e32 v103, v103
	v_mul_f32_e32 v100, v100, v101
	v_add_f32_e32 v102, 1.0, v102
	v_rcp_f32_e32 v102, v102
	v_add_f32_e32 v103, 1.0, v103
	v_rcp_f32_e32 v103, v103
	v_mov_b32_e32 v101, v92
	v_mul_f32_e32 v97, v97, v102
	v_mul_f32_e32 v97, v96, v97
	v_mul_f32_e32 v96, v99, v103
	v_mul_f32_e32 v99, v98, v96
	v_cvt_pk_bf16_f32 v96, v116, v108
	v_cvt_pk_bf16_f32 v97, v105, v97
	v_cvt_pk_bf16_f32 v98, v117, v104
	v_cvt_pk_bf16_f32 v99, v100, v99
	global_store_dwordx4 v[112:113], v[96:99], off
	v_mov_b32_e32 v100, v84
	v_mov_b32_e32 v84, v82
	v_or_b32_e32 v96, 48, v162
	v_ashrrev_i32_e32 v97, 31, v96
	v_lshl_add_u64 v[98:99], v[96:97], 3, s[8:9]
	v_mov_b32_e32 v98, v242
	v_mov_b32_e32 v99, v243
	v_mov_b32_e32 v102, v80
	v_mov_b32_e32 v80, v86
	v_mov_b32_e32 v92, v85
; __device__ __forceinline__ unsigned cvt_pk_bf16(float lo, float hi) { unsigned r; asm volatile("v_cvt_pk_bf16_f32 %0, %1, %2" : "=v"(r) : "v"(lo), "v"(hi)); return r; }
; __device__ __forceinline__ float siluf_(float x) { return x * sigmoidf_(x); }
; __device__ __forceinline__ f32x2 ln_stats(f32x2 sm) { const float mu = sm[0] * (1.f / D); const float var = fmaxf(sm[1] * (1.f / D) - mu * mu, 0.f); return (f32x2){mu, 1.0f / sqrtf(var + LN_EPS)}; }
;     __device__ __forceinline__ void operator()(const f32x4 (&acc)[2][2][4][2], const Unit& u, int wr, int wc, int fr, int fq) const {
;     ...
;         for (int ai = 0; ai < 2; ++ai)
; #pragma unroll
;             for (int m = 0; m < 4; ++m) {
;                 const int r = row0 + ai * HALF + m * 16;
;                 bf16_t* rowp = H + (size_t)r * ldh + col0;
;                 f32x2 st = (f32x2){0.f, 1.f};
;                 if (rsum) st = ln_stats(*(const f32x2*)(rsum + 2 * (size_t)r));
;                 f32x4 v0, v1;
; #pragma unroll
;                 for (int j = 0; j < 4; ++j) {
;                     const float g0 = st[1] * (acc[ai][0][m][0][j] - st[0] * s1[0][0][j]) + s2[0][0][j], u0 = st[1] * (acc[ai][1][m][0][j] - st[0] * s1[1][0][j]) + s2[1][0][j];
;                     const float g1 = st[1] * (acc[ai][0][m][1][j] - st[0] * s1[0][1][j]) + s2[0][1][j], u1 = st[1] * (acc[ai][1][m][1][j] - st[0] * s1[1][1][j]) + s2[1][1][j];
;                     v0[j] = siluf_(g0) * u0; v1[j] = siluf_(g1) * u1;
;                 }
;                 u32x4 w; w.x = cvt_pk_bf16(v0[0], v0[1]); w.y = cvt_pk_bf16(v0[2], v0[3]); w.z = cvt_pk_bf16(v1[0], v1[1]); w.w = cvt_pk_bf16(v1[2], v1[3]);
;                 *(u32x4*)rowp = w;
	v_mov_b32_e32 v85, v90
	v_mov_b32_e32 v103, v88
	v_mov_b32_e32 v88, v81
	v_mov_b32_e32 v81, v94
	v_mad_i64_i32 v[96:97], s[0:1], v96, s53, v[160:161]
	v_lshl_add_u64 v[96:97], v[96:97], 0, v[170:171]
	s_nop 0
	v_pk_mul_f32 v[98:99], v[98:99], s[20:21] op_sel_hi:[1,0]
	s_nop 0
	v_fma_f32 v82, -v98, v98, v99
	v_max_f32_e32 v82, 0, v82
	v_add_f32_e32 v82, 0x3727c5ac, v82
	v_mul_f32_e32 v86, 0x4f800000, v82
	v_cmp_gt_f32_e32 vcc, s54, v82
	v_pk_fma_f32 v[100:101], v[172:173], v[98:99], v[100:101] op_sel_hi:[1,0,1] neg_lo:[1,0,0] neg_hi:[1,0,0]
	v_pk_fma_f32 v[102:103], v[174:175], v[98:99], v[102:103] op_sel_hi:[1,0,1] neg_lo:[1,0,0] neg_hi:[1,0,0]
	v_cndmask_b32_e32 v82, v82, v86, vcc
	v_sqrt_f32_e32 v86, v82
	v_pk_fma_f32 v[88:89], v[64:65], v[98:99], v[88:89] op_sel_hi:[1,0,1] neg_lo:[1,0,0] neg_hi:[1,0,0]
	v_pk_fma_f32 v[80:81], v[166:167], v[98:99], v[80:81] op_sel_hi:[1,0,1] neg_lo:[1,0,0] neg_hi:[1,0,0]
	v_pk_fma_f32 v[92:93], v[76:77], v[98:99], v[92:93] op_sel_hi:[1,0,1] neg_lo:[1,0,0] neg_hi:[1,0,0]
	v_add_u32_e32 v90, -1, v86
	v_add_u32_e32 v94, 1, v86
	v_fma_f32 v104, -v90, v86, v82
	v_fma_f32 v105, -v94, v86, v82
	v_cmp_ge_f32_e64 s[0:1], 0, v104
	v_pk_fma_f32 v[84:85], v[168:169], v[98:99], v[84:85] op_sel_hi:[1,0,1] neg_lo:[1,0,0] neg_hi:[1,0,0]
	s_nop 0
	v_cndmask_b32_e64 v86, v86, v90, s[0:1]
	v_cmp_lt_f32_e64 s[0:1], 0, v105
	s_nop 1
	v_cndmask_b32_e64 v86, v86, v94, s[0:1]
	v_mul_f32_e32 v90, 0x37800000, v86
	v_cndmask_b32_e32 v86, v86, v90, vcc
	v_cmp_class_f32_e32 vcc, v82, v186
	s_nop 1
	v_cndmask_b32_e32 v82, v86, v82, vcc
	v_div_scale_f32 v86, s[0:1], v82, v82, 1.0
	v_rcp_f32_e32 v90, v86
	v_div_scale_f32 v94, vcc, 1.0, v82, 1.0
	v_fma_f32 v104, -v86, v90, 1.0
	v_fmac_f32_e32 v90, v104, v90
	v_mul_f32_e32 v104, v94, v90
	v_fma_f32 v105, -v86, v104, v94
	v_fmac_f32_e32 v104, v105, v90
	v_fma_f32 v86, -v86, v104, v94
	v_div_fmas_f32 v86, v86, v90, v104
	v_div_fixup_f32 v82, v86, v82, 1.0
	v_pk_fma_f32 v[100:101], v[100:101], v[82:83], v[132:133] op_sel_hi:[1,0,1]
	v_pk_fma_f32 v[102:103], v[102:103], v[82:83], v[164:165] op_sel_hi:[1,0,1]
	v_mul_f32_e32 v86, 0xbfb8aa3b, v101
	v_mul_f32_e32 v90, 0xbfb8aa3b, v103
	v_exp_f32_e32 v86, v86
	v_exp_f32_e32 v90, v90
	v_pk_fma_f32 v[88:89], v[88:89], v[82:83], v[68:69] op_sel_hi:[1,0,1]
	v_pk_fma_f32 v[80:81], v[80:81], v[82:83], v[128:129] op_sel_hi:[1,0,1]
	v_pk_fma_f32 v[92:93], v[92:93], v[82:83], v[72:73] op_sel_hi:[1,0,1]
	v_mul_f32_e32 v104, 0xbfb8aa3b, v89
	v_mul_f32_e32 v105, 0xbfb8aa3b, v81
	v_add_f32_e32 v86, 1.0, v86
	v_add_f32_e32 v90, 1.0, v90
	v_mul_f32_e32 v94, 0xbfb8aa3b, v93
	v_exp_f32_e32 v104, v104
	v_exp_f32_e32 v105, v105
	v_rcp_f32_e32 v86, v86
	v_rcp_f32_e32 v90, v90
	v_exp_f32_e32 v94, v94
	v_pk_fma_f32 v[84:85], v[84:85], v[82:83], v[136:137] op_sel_hi:[1,0,1]
	v_add_f32_e32 v104, 1.0, v104
	v_add_f32_e32 v105, 1.0, v105
	v_mul_f32_e32 v86, v101, v86
	v_mul_f32_e32 v90, v103, v90
	v_add_f32_e32 v94, 1.0, v94
	v_rcp_f32_e32 v104, v104
	v_mul_f32_e32 v100, v100, v86
	v_mul_f32_e32 v101, v102, v90
	v_rcp_f32_e32 v86, v105
	v_mul_f32_e32 v90, 0xbfb8aa3b, v85
	v_rcp_f32_e32 v94, v94
	v_exp_f32_e32 v90, v90
	v_mul_f32_e32 v89, v89, v104
	v_mul_f32_e32 v81, v81, v86
	v_mul_f32_e32 v93, v93, v94
	v_mul_f32_e32 v88, v88, v89
	v_mul_f32_e32 v89, v80, v81
	v_add_f32_e32 v80, 1.0, v90
	v_mov_b32_e32 v94, v87
	v_mul_f32_e32 v92, v92, v93
	v_rcp_f32_e32 v93, v80
	v_pk_fma_f32 v[80:81], v[78:79], v[98:99], v[94:95] op_sel_hi:[1,0,1] neg_lo:[1,0,0] neg_hi:[1,0,0]
	v_mov_b32_e32 v90, v83
	v_pk_fma_f32 v[80:81], v[80:81], v[82:83], v[74:75] op_sel_hi:[1,0,1]
	v_pk_fma_f32 v[86:87], v[66:67], v[98:99], v[90:91] op_sel_hi:[1,0,1] neg_lo:[1,0,0] neg_hi:[1,0,0]
	v_mul_f32_e32 v85, v85, v93
	v_pk_fma_f32 v[82:83], v[86:87], v[82:83], v[70:71] op_sel_hi:[1,0,1]
	v_mul_f32_e32 v86, 0xbfb8aa3b, v81
	v_exp_f32_e32 v86, v86
	v_mul_f32_e32 v87, 0xbfb8aa3b, v83
	v_exp_f32_e32 v87, v87
	v_mul_f32_e32 v84, v84, v85
	v_add_f32_e32 v86, 1.0, v86
	v_rcp_f32_e32 v86, v86
	v_add_f32_e32 v87, 1.0, v87
	v_rcp_f32_e32 v87, v87
	v_mov_b32_e32 v85, v60
	v_mul_f32_e32 v81, v81, v86
	v_mul_f32_e32 v81, v80, v81
	v_mul_f32_e32 v80, v83, v87
	v_mul_f32_e32 v83, v82, v80
	v_cvt_pk_bf16_f32 v80, v100, v92
	v_cvt_pk_bf16_f32 v81, v89, v81
	v_cvt_pk_bf16_f32 v82, v101, v88
	v_cvt_pk_bf16_f32 v83, v84, v83
	global_store_dwordx4 v[96:97], v[80:83], off
	v_mov_b32_e32 v84, v52
	v_mov_b32_e32 v52, v50
	v_add_u32_e32 v80, 0x80, v162
	v_ashrrev_i32_e32 v81, 31, v80
	v_lshl_add_u64 v[82:83], v[80:81], 3, s[8:9]
	v_mov_b32_e32 v82, v244
	v_mov_b32_e32 v83, v245
	v_mov_b32_e32 v86, v48
	v_mov_b32_e32 v48, v54
	v_mov_b32_e32 v60, v53
	v_mov_b32_e32 v53, v58
	v_mov_b32_e32 v87, v56
	v_mov_b32_e32 v56, v49
	v_mov_b32_e32 v49, v62
	v_mad_i64_i32 v[80:81], s[0:1], v80, s53, v[160:161]
	v_lshl_add_u64 v[80:81], v[80:81], 0, v[170:171]
	s_nop 0
	v_pk_mul_f32 v[82:83], v[82:83], s[20:21] op_sel_hi:[1,0]
	s_nop 0
	v_fma_f32 v50, -v82, v82, v83
	v_max_f32_e32 v50, 0, v50
	v_add_f32_e32 v50, 0x3727c5ac, v50
	v_mul_f32_e32 v54, 0x4f800000, v50
	v_cmp_gt_f32_e32 vcc, s54, v50
	v_pk_fma_f32 v[56:57], v[64:65], v[82:83], v[56:57] op_sel_hi:[1,0,1] neg_lo:[1,0,0] neg_hi:[1,0,0]
	v_pk_fma_f32 v[48:49], v[166:167], v[82:83], v[48:49] op_sel_hi:[1,0,1] neg_lo:[1,0,0] neg_hi:[1,0,0]
	v_cndmask_b32_e32 v50, v50, v54, vcc
	v_sqrt_f32_e32 v54, v50
	v_pk_fma_f32 v[86:87], v[174:175], v[82:83], v[86:87] op_sel_hi:[1,0,1] neg_lo:[1,0,0] neg_hi:[1,0,0]
	v_pk_fma_f32 v[60:61], v[76:77], v[82:83], v[60:61] op_sel_hi:[1,0,1] neg_lo:[1,0,0] neg_hi:[1,0,0]
	v_pk_fma_f32 v[84:85], v[172:173], v[82:83], v[84:85] op_sel_hi:[1,0,1] neg_lo:[1,0,0] neg_hi:[1,0,0]
; __device__ __forceinline__ unsigned cvt_pk_bf16(float lo, float hi) { unsigned r; asm volatile("v_cvt_pk_bf16_f32 %0, %1, %2" : "=v"(r) : "v"(lo), "v"(hi)); return r; }
; __device__ __forceinline__ float siluf_(float x) { return x * sigmoidf_(x); }
; __device__ __forceinline__ f32x2 ln_stats(f32x2 sm) { const float mu = sm[0] * (1.f / D); const float var = fmaxf(sm[1] * (1.f / D) - mu * mu, 0.f); return (f32x2){mu, 1.0f / sqrtf(var + LN_EPS)}; }
;     __device__ __forceinline__ void operator()(const f32x4 (&acc)[2][2][4][2], const Unit& u, int wr, int wc, int fr, int fq) const {
;     ...
;         for (int ai = 0; ai < 2; ++ai)
; #pragma unroll
;             for (int m = 0; m < 4; ++m) {
;                 const int r = row0 + ai * HALF + m * 16;
;                 bf16_t* rowp = H + (size_t)r * ldh + col0;
;                 f32x2 st = (f32x2){0.f, 1.f};
;                 if (rsum) st = ln_stats(*(const f32x2*)(rsum + 2 * (size_t)r));
;                 f32x4 v0, v1;
; #pragma unroll
;                 for (int j = 0; j < 4; ++j) {
;                     const float g0 = st[1] * (acc[ai][0][m][0][j] - st[0] * s1[0][0][j]) + s2[0][0][j], u0 = st[1] * (acc[ai][1][m][0][j] - st[0] * s1[1][0][j]) + s2[1][0][j];
;                     const float g1 = st[1] * (acc[ai][0][m][1][j] - st[0] * s1[0][1][j]) + s2[0][1][j], u1 = st[1] * (acc[ai][1][m][1][j] - st[0] * s1[1][1][j]) + s2[1][1][j];
;                     v0[j] = siluf_(g0) * u0; v1[j] = siluf_(g1) * u1;
;                 }
;                 u32x4 w; w.x = cvt_pk_bf16(v0[0], v0[1]); w.y = cvt_pk_bf16(v0[2], v0[3]); w.z = cvt_pk_bf16(v1[0], v1[1]); w.w = cvt_pk_bf16(v1[2], v1[3]);
;                 *(u32x4*)rowp = w;
	v_add_u32_e32 v58, -1, v54
	v_add_u32_e32 v62, 1, v54
	v_fma_f32 v88, -v58, v54, v50
	v_fma_f32 v89, -v62, v54, v50
	v_cmp_ge_f32_e64 s[0:1], 0, v88
	v_pk_fma_f32 v[52:53], v[168:169], v[82:83], v[52:53] op_sel_hi:[1,0,1] neg_lo:[1,0,0] neg_hi:[1,0,0]
	s_nop 0
	v_cndmask_b32_e64 v54, v54, v58, s[0:1]
	v_cmp_lt_f32_e64 s[0:1], 0, v89
	s_nop 1
	v_cndmask_b32_e64 v54, v54, v62, s[0:1]
	v_mul_f32_e32 v58, 0x37800000, v54
	v_cndmask_b32_e32 v54, v54, v58, vcc
	v_cmp_class_f32_e32 vcc, v50, v186
	s_nop 1
	v_cndmask_b32_e32 v50, v54, v50, vcc
	v_div_scale_f32 v54, s[0:1], v50, v50, 1.0
	v_rcp_f32_e32 v58, v54
	v_div_scale_f32 v62, vcc, 1.0, v50, 1.0
	v_fma_f32 v88, -v54, v58, 1.0
	v_fmac_f32_e32 v58, v88, v58
	v_mul_f32_e32 v88, v62, v58
	v_fma_f32 v89, -v54, v88, v62
	v_fmac_f32_e32 v88, v89, v58
	v_fma_f32 v54, -v54, v88, v62
	v_div_fmas_f32 v54, v54, v58, v88
	v_div_fixup_f32 v50, v54, v50, 1.0
	v_pk_fma_f32 v[56:57], v[56:57], v[50:51], v[68:69] op_sel_hi:[1,0,1]
	v_pk_fma_f32 v[48:49], v[48:49], v[50:51], v[128:129] op_sel_hi:[1,0,1]
	v_pk_fma_f32 v[86:87], v[86:87], v[50:51], v[164:165] op_sel_hi:[1,0,1]
	v_pk_fma_f32 v[60:61], v[60:61], v[50:51], v[72:73] op_sel_hi:[1,0,1]
	v_mul_f32_e32 v88, 0xbfb8aa3b, v57
	v_mul_f32_e32 v89, 0xbfb8aa3b, v49
	v_pk_fma_f32 v[84:85], v[84:85], v[50:51], v[132:133] op_sel_hi:[1,0,1]
	v_mul_f32_e32 v58, 0xbfb8aa3b, v87
	v_mul_f32_e32 v62, 0xbfb8aa3b, v61
	v_exp_f32_e32 v88, v88
	v_exp_f32_e32 v89, v89
	v_mul_f32_e32 v54, 0xbfb8aa3b, v85
	v_exp_f32_e32 v58, v58
	v_exp_f32_e32 v62, v62
	v_exp_f32_e32 v54, v54
	v_pk_fma_f32 v[52:53], v[52:53], v[50:51], v[136:137] op_sel_hi:[1,0,1]
	v_add_f32_e32 v88, 1.0, v88
	v_add_f32_e32 v89, 1.0, v89
	v_mul_f32_e32 v90, 0xbfb8aa3b, v53
	v_add_f32_e32 v58, 1.0, v58
	v_add_f32_e32 v62, 1.0, v62
	v_rcp_f32_e32 v88, v88
	v_rcp_f32_e32 v89, v89
	v_exp_f32_e32 v90, v90
	v_add_f32_e32 v54, 1.0, v54
	v_rcp_f32_e32 v58, v58
	v_rcp_f32_e32 v62, v62
	v_rcp_f32_e32 v54, v54
	v_mul_f32_e32 v57, v57, v88
	v_mul_f32_e32 v49, v49, v89
	v_mul_f32_e32 v58, v87, v58
	v_mul_f32_e32 v61, v61, v62
	v_mul_f32_e32 v56, v56, v57
	v_mul_f32_e32 v57, v48, v49
	v_add_f32_e32 v48, 1.0, v90
	v_mov_b32_e32 v62, v55
	v_mul_f32_e32 v54, v85, v54
	v_mul_f32_e32 v85, v86, v58
	v_mul_f32_e32 v60, v60, v61
	v_rcp_f32_e32 v61, v48
	v_pk_fma_f32 v[48:49], v[78:79], v[82:83], v[62:63] op_sel_hi:[1,0,1] neg_lo:[1,0,0] neg_hi:[1,0,0]
	v_mov_b32_e32 v58, v51
	v_mul_f32_e32 v84, v84, v54
	v_pk_fma_f32 v[48:49], v[48:49], v[50:51], v[74:75] op_sel_hi:[1,0,1]
	v_pk_fma_f32 v[54:55], v[66:67], v[82:83], v[58:59] op_sel_hi:[1,0,1] neg_lo:[1,0,0] neg_hi:[1,0,0]
	v_mul_f32_e32 v53, v53, v61
	v_pk_fma_f32 v[50:51], v[54:55], v[50:51], v[70:71] op_sel_hi:[1,0,1]
	v_mul_f32_e32 v54, 0xbfb8aa3b, v49
	v_exp_f32_e32 v54, v54
	v_mul_f32_e32 v55, 0xbfb8aa3b, v51
	v_exp_f32_e32 v55, v55
	v_mul_f32_e32 v52, v52, v53
	v_add_f32_e32 v54, 1.0, v54
	v_rcp_f32_e32 v54, v54
	v_add_f32_e32 v55, 1.0, v55
	v_rcp_f32_e32 v55, v55
	v_mov_b32_e32 v53, v44
	v_mul_f32_e32 v49, v49, v54
	v_mul_f32_e32 v49, v48, v49
	v_mul_f32_e32 v48, v51, v55
	v_mul_f32_e32 v51, v50, v48
	v_cvt_pk_bf16_f32 v48, v84, v60
	v_cvt_pk_bf16_f32 v49, v57, v49
	v_cvt_pk_bf16_f32 v50, v85, v56
	v_cvt_pk_bf16_f32 v51, v52, v51
	global_store_dwordx4 v[80:81], v[48:51], off
	v_mov_b32_e32 v52, v36
	v_mov_b32_e32 v36, v34
	v_add_u32_e32 v48, 0x90, v162
	v_ashrrev_i32_e32 v49, 31, v48
	v_lshl_add_u64 v[50:51], v[48:49], 3, s[8:9]
	v_mov_b32_e32 v50, v246
	v_mov_b32_e32 v51, v247
	v_mov_b32_e32 v54, v32
	v_mov_b32_e32 v32, v38
	v_mov_b32_e32 v44, v37
	v_mov_b32_e32 v37, v42
	v_mov_b32_e32 v55, v40
	v_mov_b32_e32 v40, v33
	v_mov_b32_e32 v33, v46
	v_mad_i64_i32 v[48:49], s[0:1], v48, s53, v[160:161]
	v_lshl_add_u64 v[48:49], v[48:49], 0, v[170:171]
	s_nop 0
	v_pk_mul_f32 v[50:51], v[50:51], s[20:21] op_sel_hi:[1,0]
	s_nop 0
	v_fma_f32 v34, -v50, v50, v51
	v_max_f32_e32 v34, 0, v34
	v_add_f32_e32 v34, 0x3727c5ac, v34
	v_mul_f32_e32 v38, 0x4f800000, v34
	v_cmp_gt_f32_e32 vcc, s54, v34
	v_pk_fma_f32 v[40:41], v[64:65], v[50:51], v[40:41] op_sel_hi:[1,0,1] neg_lo:[1,0,0] neg_hi:[1,0,0]
	v_pk_fma_f32 v[32:33], v[166:167], v[50:51], v[32:33] op_sel_hi:[1,0,1] neg_lo:[1,0,0] neg_hi:[1,0,0]
	v_cndmask_b32_e32 v34, v34, v38, vcc
	v_sqrt_f32_e32 v38, v34
	v_pk_fma_f32 v[54:55], v[174:175], v[50:51], v[54:55] op_sel_hi:[1,0,1] neg_lo:[1,0,0] neg_hi:[1,0,0]
	v_pk_fma_f32 v[44:45], v[76:77], v[50:51], v[44:45] op_sel_hi:[1,0,1] neg_lo:[1,0,0] neg_hi:[1,0,0]
	v_pk_fma_f32 v[52:53], v[172:173], v[50:51], v[52:53] op_sel_hi:[1,0,1] neg_lo:[1,0,0] neg_hi:[1,0,0]
	v_add_u32_e32 v42, -1, v38
	v_add_u32_e32 v46, 1, v38
	v_fma_f32 v56, -v42, v38, v34
	v_fma_f32 v57, -v46, v38, v34
	v_cmp_ge_f32_e64 s[0:1], 0, v56
	v_pk_fma_f32 v[36:37], v[168:169], v[50:51], v[36:37] op_sel_hi:[1,0,1] neg_lo:[1,0,0] neg_hi:[1,0,0]
	s_nop 0
	v_cndmask_b32_e64 v38, v38, v42, s[0:1]
	v_cmp_lt_f32_e64 s[0:1], 0, v57
	s_nop 1
	v_cndmask_b32_e64 v38, v38, v46, s[0:1]
	v_mul_f32_e32 v42, 0x37800000, v38
	v_cndmask_b32_e32 v38, v38, v42, vcc
	v_cmp_class_f32_e32 vcc, v34, v186
	s_nop 1
	v_cndmask_b32_e32 v34, v38, v34, vcc
	v_div_scale_f32 v38, s[0:1], v34, v34, 1.0
	v_rcp_f32_e32 v42, v38
	v_div_scale_f32 v46, vcc, 1.0, v34, 1.0
	v_fma_f32 v56, -v38, v42, 1.0
	v_fmac_f32_e32 v42, v56, v42
	v_mul_f32_e32 v56, v46, v42
	v_fma_f32 v57, -v38, v56, v46
	v_fmac_f32_e32 v56, v57, v42
	v_fma_f32 v38, -v38, v56, v46
	v_div_fmas_f32 v38, v38, v42, v56
	v_div_fixup_f32 v34, v38, v34, 1.0
	v_pk_fma_f32 v[40:41], v[40:41], v[34:35], v[68:69] op_sel_hi:[1,0,1]
	v_pk_fma_f32 v[32:33], v[32:33], v[34:35], v[128:129] op_sel_hi:[1,0,1]
; __device__ __forceinline__ unsigned cvt_pk_bf16(float lo, float hi) { unsigned r; asm volatile("v_cvt_pk_bf16_f32 %0, %1, %2" : "=v"(r) : "v"(lo), "v"(hi)); return r; }
; __device__ __forceinline__ float siluf_(float x) { return x * sigmoidf_(x); }
; __device__ __forceinline__ f32x2 ln_stats(f32x2 sm) { const float mu = sm[0] * (1.f / D); const float var = fmaxf(sm[1] * (1.f / D) - mu * mu, 0.f); return (f32x2){mu, 1.0f / sqrtf(var + LN_EPS)}; }
;     __device__ __forceinline__ void operator()(const f32x4 (&acc)[2][2][4][2], const Unit& u, int wr, int wc, int fr, int fq) const {
;     ...
;         for (int ai = 0; ai < 2; ++ai)
; #pragma unroll
;             for (int m = 0; m < 4; ++m) {
;                 const int r = row0 + ai * HALF + m * 16;
;                 bf16_t* rowp = H + (size_t)r * ldh + col0;
;                 f32x2 st = (f32x2){0.f, 1.f};
;                 if (rsum) st = ln_stats(*(const f32x2*)(rsum + 2 * (size_t)r));
;                 f32x4 v0, v1;
; #pragma unroll
;                 for (int j = 0; j < 4; ++j) {
;                     const float g0 = st[1] * (acc[ai][0][m][0][j] - st[0] * s1[0][0][j]) + s2[0][0][j], u0 = st[1] * (acc[ai][1][m][0][j] - st[0] * s1[1][0][j]) + s2[1][0][j];
;                     const float g1 = st[1] * (acc[ai][0][m][1][j] - st[0] * s1[0][1][j]) + s2[0][1][j], u1 = st[1] * (acc[ai][1][m][1][j] - st[0] * s1[1][1][j]) + s2[1][1][j];
;                     v0[j] = siluf_(g0) * u0; v1[j] = siluf_(g1) * u1;
;                 }
;                 u32x4 w; w.x = cvt_pk_bf16(v0[0], v0[1]); w.y = cvt_pk_bf16(v0[2], v0[3]); w.z = cvt_pk_bf16(v1[0], v1[1]); w.w = cvt_pk_bf16(v1[2], v1[3]);
;                 *(u32x4*)rowp = w;
	v_pk_fma_f32 v[54:55], v[54:55], v[34:35], v[164:165] op_sel_hi:[1,0,1]
	v_pk_fma_f32 v[44:45], v[44:45], v[34:35], v[72:73] op_sel_hi:[1,0,1]
	v_mul_f32_e32 v56, 0xbfb8aa3b, v41
	v_mul_f32_e32 v57, 0xbfb8aa3b, v33
	v_pk_fma_f32 v[52:53], v[52:53], v[34:35], v[132:133] op_sel_hi:[1,0,1]
	v_mul_f32_e32 v42, 0xbfb8aa3b, v55
	v_mul_f32_e32 v46, 0xbfb8aa3b, v45
	v_exp_f32_e32 v56, v56
	v_exp_f32_e32 v57, v57
	v_mul_f32_e32 v38, 0xbfb8aa3b, v53
	v_exp_f32_e32 v42, v42
	v_exp_f32_e32 v46, v46
	v_exp_f32_e32 v38, v38
	v_pk_fma_f32 v[36:37], v[36:37], v[34:35], v[136:137] op_sel_hi:[1,0,1]
	v_add_f32_e32 v56, 1.0, v56
	v_add_f32_e32 v57, 1.0, v57
	v_mul_f32_e32 v58, 0xbfb8aa3b, v37
	v_add_f32_e32 v42, 1.0, v42
	v_add_f32_e32 v46, 1.0, v46
	v_rcp_f32_e32 v56, v56
	v_rcp_f32_e32 v57, v57
	v_exp_f32_e32 v58, v58
	v_add_f32_e32 v38, 1.0, v38
	v_rcp_f32_e32 v42, v42
	v_rcp_f32_e32 v46, v46
	v_rcp_f32_e32 v38, v38
	v_mul_f32_e32 v41, v41, v56
	v_mul_f32_e32 v33, v33, v57
	v_mul_f32_e32 v42, v55, v42
	v_mul_f32_e32 v45, v45, v46
	v_mul_f32_e32 v40, v40, v41
	v_mul_f32_e32 v41, v32, v33
	v_add_f32_e32 v32, 1.0, v58
	v_mov_b32_e32 v46, v39
	v_mul_f32_e32 v38, v53, v38
	v_mul_f32_e32 v53, v54, v42
	v_mul_f32_e32 v44, v44, v45
	v_rcp_f32_e32 v45, v32
	v_pk_fma_f32 v[32:33], v[78:79], v[50:51], v[46:47] op_sel_hi:[1,0,1] neg_lo:[1,0,0] neg_hi:[1,0,0]
	v_mov_b32_e32 v42, v35
	v_mul_f32_e32 v52, v52, v38
	v_pk_fma_f32 v[32:33], v[32:33], v[34:35], v[74:75] op_sel_hi:[1,0,1]
	v_pk_fma_f32 v[38:39], v[66:67], v[50:51], v[42:43] op_sel_hi:[1,0,1] neg_lo:[1,0,0] neg_hi:[1,0,0]
	v_mul_f32_e32 v37, v37, v45
	v_pk_fma_f32 v[34:35], v[38:39], v[34:35], v[70:71] op_sel_hi:[1,0,1]
	v_mul_f32_e32 v38, 0xbfb8aa3b, v33
	v_exp_f32_e32 v38, v38
	v_mul_f32_e32 v39, 0xbfb8aa3b, v35
	v_exp_f32_e32 v39, v39
	v_mul_f32_e32 v36, v36, v37
	v_add_f32_e32 v38, 1.0, v38
	v_rcp_f32_e32 v38, v38
	v_add_f32_e32 v39, 1.0, v39
	v_rcp_f32_e32 v39, v39
	v_mov_b32_e32 v37, v24
	v_mul_f32_e32 v33, v33, v38
	v_mul_f32_e32 v33, v32, v33
	v_mul_f32_e32 v32, v35, v39
	v_mul_f32_e32 v35, v34, v32
	v_cvt_pk_bf16_f32 v32, v52, v44
	v_cvt_pk_bf16_f32 v33, v41, v33
	v_cvt_pk_bf16_f32 v34, v53, v40
	v_cvt_pk_bf16_f32 v35, v36, v35
	global_store_dwordx4 v[48:49], v[32:35], off
	v_mov_b32_e32 v38, v16
	v_mov_b32_e32 v39, v20
	v_add_u32_e32 v32, 0xa0, v162
	v_ashrrev_i32_e32 v33, 31, v32
	v_lshl_add_u64 v[34:35], v[32:33], 3, s[8:9]
	v_mov_b32_e32 v34, v248
	v_mov_b32_e32 v35, v249
	v_mov_b32_e32 v20, v17
	v_mov_b32_e32 v16, v30
	v_mov_b32_e32 v17, v26
	v_mov_b32_e32 v26, v31
	v_mad_i64_i32 v[30:31], s[0:1], v32, s53, v[160:161]
	v_mov_b32_e32 v36, v28
	v_mov_b32_e32 v28, v18
	v_mov_b32_e32 v24, v29
	v_mov_b32_e32 v29, v22
	v_lshl_add_u64 v[30:31], v[30:31], 0, v[170:171]
	s_nop 0
	v_pk_mul_f32 v[32:33], v[34:35], s[20:21] op_sel_hi:[1,0]
	s_nop 0
	v_fma_f32 v18, -v32, v32, v33
	v_max_f32_e32 v18, 0, v18
	v_add_f32_e32 v18, 0x3727c5ac, v18
	v_mul_f32_e32 v22, 0x4f800000, v18
	v_cmp_gt_f32_e32 vcc, s54, v18
	v_pk_fma_f32 v[34:35], v[172:173], v[32:33], v[36:37] op_sel_hi:[1,0,1] neg_lo:[1,0,0] neg_hi:[1,0,0]
	v_pk_fma_f32 v[36:37], v[174:175], v[32:33], v[38:39] op_sel_hi:[1,0,1] neg_lo:[1,0,0] neg_hi:[1,0,0]
	v_cndmask_b32_e32 v18, v18, v22, vcc
	v_sqrt_f32_e32 v22, v18
	v_pk_fma_f32 v[16:17], v[166:167], v[32:33], v[16:17] op_sel_hi:[1,0,1] neg_lo:[1,0,0] neg_hi:[1,0,0]
	v_pk_fma_f32 v[24:25], v[76:77], v[32:33], v[24:25] op_sel_hi:[1,0,1] neg_lo:[1,0,0] neg_hi:[1,0,0]
	v_pk_fma_f32 v[20:21], v[64:65], v[32:33], v[20:21] op_sel_hi:[1,0,1] neg_lo:[1,0,0] neg_hi:[1,0,0]
	v_add_u32_e32 v38, -1, v22
	v_add_u32_e32 v39, 1, v22
	v_fma_f32 v40, -v38, v22, v18
	v_fma_f32 v41, -v39, v22, v18
	v_cmp_ge_f32_e64 s[0:1], 0, v40
	v_pk_fma_f32 v[28:29], v[168:169], v[32:33], v[28:29] op_sel_hi:[1,0,1] neg_lo:[1,0,0] neg_hi:[1,0,0]
	s_nop 0
	v_cndmask_b32_e64 v22, v22, v38, s[0:1]
	v_cmp_lt_f32_e64 s[0:1], 0, v41
	s_nop 1
	v_cndmask_b32_e64 v22, v22, v39, s[0:1]
	v_mul_f32_e32 v38, 0x37800000, v22
	v_cndmask_b32_e32 v22, v22, v38, vcc
	v_cmp_class_f32_e32 vcc, v18, v186
	s_nop 1
	v_cndmask_b32_e32 v18, v22, v18, vcc
	v_div_scale_f32 v22, s[0:1], v18, v18, 1.0
	v_rcp_f32_e32 v38, v22
	v_div_scale_f32 v39, vcc, 1.0, v18, 1.0
	v_fma_f32 v40, -v22, v38, 1.0
	v_fmac_f32_e32 v38, v40, v38
	v_mul_f32_e32 v40, v39, v38
	v_fma_f32 v41, -v22, v40, v39
	v_fmac_f32_e32 v40, v41, v38
	v_fma_f32 v22, -v22, v40, v39
	v_div_fmas_f32 v22, v22, v38, v40
	v_div_fixup_f32 v18, v22, v18, 1.0
	v_pk_fma_f32 v[34:35], v[34:35], v[18:19], v[132:133] op_sel_hi:[1,0,1]
	v_pk_fma_f32 v[36:37], v[36:37], v[18:19], v[164:165] op_sel_hi:[1,0,1]
	v_pk_fma_f32 v[16:17], v[16:17], v[18:19], v[128:129] op_sel_hi:[1,0,1]
	v_pk_fma_f32 v[24:25], v[24:25], v[18:19], v[72:73] op_sel_hi:[1,0,1]
	v_pk_fma_f32 v[20:21], v[20:21], v[18:19], v[68:69] op_sel_hi:[1,0,1]
	v_mul_f32_e32 v22, 0xbfb8aa3b, v35
	v_mul_f32_e32 v38, 0xbfb8aa3b, v37
	v_mul_f32_e32 v41, 0xbfb8aa3b, v17
	v_mul_f32_e32 v39, 0xbfb8aa3b, v25
	v_mul_f32_e32 v40, 0xbfb8aa3b, v21
	v_exp_f32_e32 v22, v22
	v_exp_f32_e32 v38, v38
	v_exp_f32_e32 v41, v41
	v_exp_f32_e32 v39, v39
	v_exp_f32_e32 v40, v40
	v_add_f32_e32 v22, 1.0, v22
	v_add_f32_e32 v38, 1.0, v38
	v_add_f32_e32 v41, 1.0, v41
	v_add_f32_e32 v39, 1.0, v39
	v_add_f32_e32 v40, 1.0, v40
	v_rcp_f32_e32 v22, v22
	v_rcp_f32_e32 v38, v38
	v_rcp_f32_e32 v41, v41
	v_rcp_f32_e32 v39, v39
	v_rcp_f32_e32 v40, v40
	v_mul_f32_e32 v22, v35, v22
	v_mul_f32_e32 v35, v37, v38
	v_mul_f32_e32 v17, v17, v41
	v_mul_f32_e32 v25, v25, v39
	v_mul_f32_e32 v21, v21, v40
	v_mul_f32_e32 v34, v34, v22
	v_mul_f32_e32 v35, v36, v35
	v_mul_f32_e32 v36, v16, v17
; __device__ __forceinline__ unsigned cvt_pk_bf16(float lo, float hi) { unsigned r; asm volatile("v_cvt_pk_bf16_f32 %0, %1, %2" : "=v"(r) : "v"(lo), "v"(hi)); return r; }
; __device__ __forceinline__ float siluf_(float x) { return x * sigmoidf_(x); }
; #define PG8_BAR __builtin_amdgcn_s_barrier()
; template <class Sched, class Epi, bool ALIGN_EPI, bool SP2>
; __device__ __forceinline__ void gemm_phase(LAS unsigned char* lds, const int K, const int lda, const int ldb, const Sched& S, const Epi& E) {
;     ...
;         if constexpr (ALIGN_EPI) { if (wr == 0) PG8_BAR; }
;         E(acc, cur, wr, wc, fr, fq);
;         if (!has_next) break;
;         bool keep = false;
;         if constexpr (Epi::CAN_KEEP) keep = (cur.kind < 2);
;         if (!keep) {
; #pragma unroll
;         for (int a = 0; a < 2; ++a)
; #pragma unroll
;             for (int b = 0; b < 2; ++b)
; #pragma unroll
;                 for (int m = 0; m < 4; ++m)
; #pragma unroll
;                     for (int n = 0; n < 2; ++n) acc[a][b][m][n] = (f32x4){0.f, 0.f, 0.f, 0.f};
;         }
;         cur = nxt; cA = nA; cB = nB; ++ui;
;         if constexpr (ALIGN_EPI) { if (wr == 1) PG8_BAR; }
;     __device__ __forceinline__ void operator()(const f32x4 (&acc)[2][2][4][2], const Unit& u, int wr, int wc, int fr, int fq) const {
;     ...
;         for (int ai = 0; ai < 2; ++ai)
; #pragma unroll
;             for (int m = 0; m < 4; ++m) {
;                 const int r = row0 + ai * HALF + m * 16;
;                 bf16_t* rowp = H + (size_t)r * ldh + col0;
;                 f32x2 st = (f32x2){0.f, 1.f};
;                 if (rsum) st = ln_stats(*(const f32x2*)(rsum + 2 * (size_t)r));
;                 f32x4 v0, v1;
; #pragma unroll
;                 for (int j = 0; j < 4; ++j) {
;                     const float g0 = st[1] * (acc[ai][0][m][0][j] - st[0] * s1[0][0][j]) + s2[0][0][j], u0 = st[1] * (acc[ai][1][m][0][j] - st[0] * s1[1][0][j]) + s2[1][0][j];
;                     const float g1 = st[1] * (acc[ai][0][m][1][j] - st[0] * s1[0][1][j]) + s2[0][1][j], u1 = st[1] * (acc[ai][1][m][1][j] - st[0] * s1[1][1][j]) + s2[1][1][j];
;                     v0[j] = siluf_(g0) * u0; v1[j] = siluf_(g1) * u1;
;                 }
;                 u32x4 w; w.x = cvt_pk_bf16(v0[0], v0[1]); w.y = cvt_pk_bf16(v0[2], v0[3]); w.z = cvt_pk_bf16(v1[0], v1[1]); w.w = cvt_pk_bf16(v1[2], v1[3]);
;                 *(u32x4*)rowp = w;
	v_pk_fma_f32 v[16:17], v[78:79], v[32:33], v[26:27] op_sel_hi:[1,0,1] neg_lo:[1,0,0] neg_hi:[1,0,0]
	v_mov_b32_e32 v22, v19
	v_mul_f32_e32 v24, v24, v25
	v_mul_f32_e32 v25, v20, v21
	v_pk_fma_f32 v[16:17], v[16:17], v[18:19], v[74:75] op_sel_hi:[1,0,1]
	v_pk_fma_f32 v[20:21], v[66:67], v[32:33], v[22:23] op_sel_hi:[1,0,1] neg_lo:[1,0,0] neg_hi:[1,0,0]
	v_pk_fma_f32 v[28:29], v[28:29], v[18:19], v[136:137] op_sel_hi:[1,0,1]
	v_pk_fma_f32 v[18:19], v[20:21], v[18:19], v[70:71] op_sel_hi:[1,0,1]
	v_mul_f32_e32 v20, 0xbfb8aa3b, v17
	v_exp_f32_e32 v20, v20
	v_mul_f32_e32 v21, 0xbfb8aa3b, v19
	v_mul_f32_e32 v42, 0xbfb8aa3b, v29
	v_exp_f32_e32 v21, v21
	v_exp_f32_e32 v42, v42
	v_add_f32_e32 v20, 1.0, v20
	v_rcp_f32_e32 v20, v20
	v_add_f32_e32 v21, 1.0, v21
	v_add_f32_e32 v42, 1.0, v42
	v_rcp_f32_e32 v21, v21
	v_rcp_f32_e32 v42, v42
	v_mul_f32_e32 v17, v17, v20
	v_mul_f32_e32 v17, v16, v17
	v_mul_f32_e32 v16, v19, v21
	v_mul_f32_e32 v22, v29, v42
	v_mul_f32_e32 v19, v18, v16
	v_cvt_pk_bf16_f32 v16, v34, v24
	v_mul_f32_e32 v22, v28, v22
	v_cvt_pk_bf16_f32 v17, v36, v17
	v_cvt_pk_bf16_f32 v18, v35, v25
	v_cvt_pk_bf16_f32 v19, v22, v19
	global_store_dwordx4 v[30:31], v[16:19], off
	v_mov_b32_e32 v22, v4
	v_mov_b32_e32 v23, v0
	v_add_u32_e32 v16, 0xb0, v162
	v_ashrrev_i32_e32 v17, 31, v16
	v_lshl_add_u64 v[18:19], v[16:17], 3, s[8:9]
	v_mov_b32_e32 v18, v250
	v_mov_b32_e32 v19, v251
	v_mov_b32_e32 v0, v5
	v_mov_b32_e32 v4, v14
	v_mov_b32_e32 v5, v10
	v_mov_b32_e32 v10, v15
	v_mov_b32_e32 v20, v12
	v_mov_b32_e32 v21, v8
	v_mov_b32_e32 v8, v13
	v_mov_b32_e32 v12, v6
	v_mov_b32_e32 v13, v2
	v_mov_b32_e32 v2, v7
	v_mad_i64_i32 v[6:7], s[0:1], v16, s53, v[160:161]
	v_lshl_add_u64 v[6:7], v[6:7], 0, v[170:171]
	s_nop 0
	v_pk_mul_f32 v[14:15], v[18:19], s[20:21] op_sel_hi:[1,0]
	s_nop 0
	v_fma_f32 v24, -v14, v14, v15
	v_pk_fma_f32 v[16:17], v[172:173], v[14:15], v[20:21] op_sel_hi:[1,0,1] neg_lo:[1,0,0] neg_hi:[1,0,0]
	v_max_f32_e32 v20, 0, v24
	v_add_f32_e32 v20, 0x3727c5ac, v20
	v_mul_f32_e32 v21, 0x4f800000, v20
	v_cmp_gt_f32_e32 vcc, s54, v20
	v_pk_fma_f32 v[18:19], v[174:175], v[14:15], v[22:23] op_sel_hi:[1,0,1] neg_lo:[1,0,0] neg_hi:[1,0,0]
	v_pk_fma_f32 v[8:9], v[76:77], v[14:15], v[8:9] op_sel_hi:[1,0,1] neg_lo:[1,0,0] neg_hi:[1,0,0]
	v_cndmask_b32_e32 v20, v20, v21, vcc
	v_sqrt_f32_e32 v21, v20
	v_pk_fma_f32 v[0:1], v[64:65], v[14:15], v[0:1] op_sel_hi:[1,0,1] neg_lo:[1,0,0] neg_hi:[1,0,0]
	v_pk_fma_f32 v[4:5], v[166:167], v[14:15], v[4:5] op_sel_hi:[1,0,1] neg_lo:[1,0,0] neg_hi:[1,0,0]
	v_pk_fma_f32 v[12:13], v[168:169], v[14:15], v[12:13] op_sel_hi:[1,0,1] neg_lo:[1,0,0] neg_hi:[1,0,0]
	v_add_u32_e32 v22, -1, v21
	v_add_u32_e32 v23, 1, v21
	v_fma_f32 v24, -v22, v21, v20
	v_fma_f32 v25, -v23, v21, v20
	v_cmp_ge_f32_e64 s[0:1], 0, v24
	v_pk_fma_f32 v[10:11], v[78:79], v[14:15], v[10:11] op_sel_hi:[1,0,1] neg_lo:[1,0,0] neg_hi:[1,0,0]
	s_nop 0
	v_cndmask_b32_e64 v21, v21, v22, s[0:1]
	v_cmp_lt_f32_e64 s[0:1], 0, v25
	s_nop 1
	v_cndmask_b32_e64 v21, v21, v23, s[0:1]
	v_mul_f32_e32 v22, 0x37800000, v21
	v_cndmask_b32_e32 v21, v21, v22, vcc
	v_cmp_class_f32_e32 vcc, v20, v186
	s_nop 1
	v_cndmask_b32_e32 v20, v21, v20, vcc
	v_div_scale_f32 v21, s[0:1], v20, v20, 1.0
	v_rcp_f32_e32 v22, v21
	v_div_scale_f32 v23, vcc, 1.0, v20, 1.0
	s_mov_b64 s[0:1], -1
	v_fma_f32 v24, -v21, v22, 1.0
	v_fmac_f32_e32 v22, v24, v22
	v_mul_f32_e32 v24, v23, v22
	v_fma_f32 v25, -v21, v24, v23
	v_fmac_f32_e32 v24, v25, v22
	v_fma_f32 v21, -v21, v24, v23
	v_div_fmas_f32 v21, v21, v22, v24
	v_div_fixup_f32 v20, v21, v20, 1.0
	v_pk_fma_f32 v[8:9], v[8:9], v[20:21], v[72:73] op_sel_hi:[1,0,1]
	v_pk_fma_f32 v[0:1], v[0:1], v[20:21], v[68:69] op_sel_hi:[1,0,1]
	v_mul_f32_e32 v23, 0xbfb8aa3b, v9
	v_mul_f32_e32 v24, 0xbfb8aa3b, v1
	v_pk_fma_f32 v[16:17], v[16:17], v[20:21], v[132:133] op_sel_hi:[1,0,1]
	v_exp_f32_e32 v23, v23
	v_exp_f32_e32 v24, v24
	v_pk_fma_f32 v[18:19], v[18:19], v[20:21], v[164:165] op_sel_hi:[1,0,1]
	v_pk_fma_f32 v[4:5], v[4:5], v[20:21], v[128:129] op_sel_hi:[1,0,1]
	v_pk_fma_f32 v[12:13], v[12:13], v[20:21], v[136:137] op_sel_hi:[1,0,1]
	v_pk_fma_f32 v[10:11], v[10:11], v[20:21], v[74:75] op_sel_hi:[1,0,1]
	v_mul_f32_e32 v21, 0xbfb8aa3b, v17
	v_exp_f32_e32 v21, v21
	v_add_f32_e32 v23, 1.0, v23
	v_add_f32_e32 v24, 1.0, v24
	v_rcp_f32_e32 v23, v23
	v_rcp_f32_e32 v24, v24
	v_add_f32_e32 v21, 1.0, v21
	v_rcp_f32_e32 v21, v21
	v_mul_f32_e32 v9, v9, v23
	v_mul_f32_e32 v1, v1, v24
	v_mul_f32_e32 v8, v8, v9
	v_mul_f32_e32 v9, v0, v1
	v_pk_fma_f32 v[0:1], v[66:67], v[14:15], v[2:3] op_sel_hi:[1,0,1] neg_lo:[1,0,0] neg_hi:[1,0,0]
	v_mul_f32_e32 v25, 0xbfb8aa3b, v5
	v_pk_fma_f32 v[0:1], v[0:1], v[20:21], v[70:71] op_sel_hi:[1,0,1]
	v_mul_f32_e32 v2, 0xbfb8aa3b, v11
	v_mul_f32_e32 v3, 0xbfb8aa3b, v1
	v_mul_f32_e32 v22, 0xbfb8aa3b, v19
	v_mul_f32_e32 v26, 0xbfb8aa3b, v13
	v_exp_f32_e32 v25, v25
	v_exp_f32_e32 v2, v2
	v_exp_f32_e32 v3, v3
	v_exp_f32_e32 v22, v22
	v_exp_f32_e32 v26, v26
	v_add_f32_e32 v25, 1.0, v25
	v_add_f32_e32 v2, 1.0, v2
	v_add_f32_e32 v3, 1.0, v3
	v_add_f32_e32 v22, 1.0, v22
	v_add_f32_e32 v26, 1.0, v26
	v_rcp_f32_e32 v25, v25
	v_rcp_f32_e32 v2, v2
	v_rcp_f32_e32 v3, v3
	v_rcp_f32_e32 v22, v22
	v_rcp_f32_e32 v26, v26
	v_mul_f32_e32 v5, v5, v25
	v_mul_f32_e32 v2, v11, v2
	v_mul_f32_e32 v1, v1, v3
	v_mul_f32_e32 v17, v17, v21
	v_mul_f32_e32 v19, v19, v22
	v_mul_f32_e32 v4, v4, v5
	v_mul_f32_e32 v5, v13, v26
	v_mul_f32_e32 v2, v10, v2
	v_mul_f32_e32 v3, v0, v1
	s_andn2_b64 vcc, exec, s[22:23]
	v_mul_f32_e32 v16, v16, v17
	v_mul_f32_e32 v17, v18, v19
	v_mul_f32_e32 v5, v12, v5
	v_cvt_pk_bf16_f32 v0, v16, v8
	v_cvt_pk_bf16_f32 v1, v4, v2
	v_cvt_pk_bf16_f32 v2, v17, v9
	v_cvt_pk_bf16_f32 v3, v5, v3
	global_store_dwordx4 v[6:7], v[0:3], off
	s_cbranch_vccnz .LBB0_1029
	s_add_i32 s101, s101, 1
	s_cmp_gt_u32 s101, 4
	s_cbranch_scc1 .Lts_skip_p10
	v_readlane_b32 s100, v255, 13
	s_nop 4
	s_cmp_lg_u32 s100, 0
	s_cbranch_scc1 .Lts_wait_p10
	s_mov_b64 s[98:99], exec
	s_mov_b64 exec, 1
	v_mov_b32_e32 v253, 0x26fc0
	ds_read_b32 v253, v253
	s_getreg_b32 s100, hwreg(HW_REG_XCC_ID, 0, 4)
	s_lshl_b32 s100, s100, 8
	s_add_u32 s100, s100, 0x2b1a0040
	v_mov_b32_e32 v252, s100
	s_waitcnt lgkmcnt(0)
	v_readfirstlane_b32 s100, v253
	v_mov_b32_e32 v253, 1
	s_add_i32 vcc_lo, s101, 4
	s_mul_i32 s100, s100, vcc_lo
	global_atomic_add v252, v253, s[92:93]
	s_mov_b32 vcc_lo, 0

; #define PG8_BAR __builtin_amdgcn_s_barrier()
; template <class Sched, class Epi, bool ALIGN_EPI, bool SP2>
; __device__ __forceinline__ void gemm_phase(LAS unsigned char* lds, const int K, const int lda, const int ldb, const Sched& S, const Epi& E) {
;     ...
;         cur = nxt; cA = nA; cB = nB; ++ui;
;         if constexpr (ALIGN_EPI) { if (wr == 1) PG8_BAR; }
;     }
.Lts_skip_p10:
	s_andn2_b64 vcc, exec, s[4:5]
	s_cbranch_vccnz .LBB0_1028
	s_barrier
	s_branch .LBB0_1028
